# v33 with the weight warm-up covering the first 8 K-steps (1 KiB per weight row) instead of 4
# baseline (speedup 1.0000x reference)
;     __device__ void init(int M, int N, int G_, int c_) { nM = M / BM; nN = N / BM; nwg = nM * nN; G = launder_s(G_); c = launder_s(c_); }
; #define GRID_BAR() do { XcdBarrier b_; b_.bar = (unsigned*)(args.ws + WS_CTL); b_.x = xb_xcc_id(); b_.st = (volatile LAS unsigned*)(lds + LDS_BYTES - 64); xcd_barrier(b_); } while (0)
; #define GRID_BAR() grid.sync()
; __global__ void __launch_bounds__(NTHR, 2) mk_fwd(Args args) {
;     ...
;             lru_scan1(AB, BB, XC, INF(ib + 8), PE, bid, G);
;             GRID_BAR();
;             lru_scan2(AB, BB, XC, INF(ib + 8), PE, GATE, Y, bid, G);
;             GRID_BAR();
;             { pg8::Gemm g{Y, (const bf16_t*)(wm + WM_B_O), T, D, D, D, D, 0, 0}; pg8::StaticOrder S; S.init(T, D, G, bid); pg8::EpiResidual E{hin, out, HB0, SSQ0, PTAB, nullptr}; pg8::gemm_phase(lds, g, S, E); }
.LBB0_740:
	s_or_b64 exec, exec, s[4:5]
	s_waitcnt lgkmcnt(0)
	s_barrier
	s_load_dwordx2 s[4:5], s[8:9], 0x40
	s_cmp_ge_u32 s74, 32
	s_cbranch_scc1 .Lwpf_i
	s_lshl_b32 s100, s74, 9
	v_add_u32_e32 v130, s100, v246
	v_lshrrev_b32_e32 v131, 3, v130
	v_and_b32_e32 v130, 7, v130
	v_lshlrev_b32_e32 v130, 7, v130
	v_lshl_add_u32 v130, v131, 12, v130
	s_add_u32 s100, s38, 0x14900000
	s_addc_u32 s101, s39, 0
	s_mov_b32 m0, 0x21000
	s_nop 0
	global_load_lds_dword v130, s[100:101]

; #define PG8_STAGE(bufoff, gbase, voff) do { _Pragma("unroll") for (int _i = 0; _i < 2; ++_i) \
;         __builtin_amdgcn_global_load_lds((const unsigned*)((const char*)(gbase) + (voff)[_i]), (LAS unsigned*)(lds + (bufoff) + ldsw + _i * 8192), 16, 0, 0); } while (0)
; #define PG8_LDA(dst, b, h) do { _Pragma("unroll") for (int m = 0; m < 4; ++m) _Pragma("unroll") for (int k = 0; k < 2; ++k) dst[m][k] = *(const LAS bf16x8*)(lds + PG8_SA(b, h) + aoff + m * 2048 + k * 1024); } while (0)
; #define PG8_LDB(dst, b, h) do { _Pragma("unroll") for (int n = 0; n < 2; ++n) _Pragma("unroll") for (int k = 0; k < 2; ++k) dst[n][k] = *(const LAS bf16x8*)(lds + PG8_SB(b, h) + boff + n * 2048 + k * 1024); } while (0)
; #define PG8_MMA(ai, bj, At, Bt) do { __builtin_amdgcn_s_setprio(1); _Pragma("unroll") for (int m = 0; m < 4; ++m) _Pragma("unroll") for (int n = 0; n < 2; ++n) _Pragma("unroll") for (int k = 0; k < 2; ++k) \
;         acc[ai][bj][m][n] = __builtin_amdgcn_mfma_f32_16x16x32_bf16(Bt[n][k], At[m][k], acc[ai][bj][m][n], 0, 0, 0); __builtin_amdgcn_s_setprio(0); } while (0)
; #define PG8_WAIT_V(n) asm volatile("s_waitcnt vmcnt(" #n ")" ::: "memory")
; #define PG8_WAIT_L(n) asm volatile("s_waitcnt lgkmcnt(" #n ")" ::: "memory")
; #define PG8_BAR __builtin_amdgcn_s_barrier()
; #define PG8_SCHED __builtin_amdgcn_sched_barrier(0)
; template <class Epi>
; __device__ __forceinline__ void gemm_phase(LAS unsigned char* lds, const Gemm g, const StaticOrder& S, const Epi& E) {
;     ...
;             PG8_LDB(B0, 0, 0); PG8_LDB(B1, 0, 1); PG8_SCHED; PG8_LDA(At, 0, 0); PG8_STAGE(PG8_SA(1, 1), a1 + hstepA, voffA);
;             PG8_WAIT_V(8); PG8_WAIT_L(0); PG8_BAR; PG8_MMA(0, 0, At, B0); PG8_MMA(0, 1, At, B1); PG8_BAR; PG8_SCHED;
;             PG8_LDA(At, 0, 1); PG8_STAGE(PG8_SB(0, 0), b2, voffB); PG8_STAGE(PG8_SB(0, 1), b2 + hstepB, voffB); PG8_STAGE(PG8_SA(0, 0), a2, voffA);
;             PG8_WAIT_V(8); PG8_WAIT_L(0); PG8_BAR; PG8_MMA(1, 0, At, B0); PG8_MMA(1, 1, At, B1); PG8_BAR; PG8_SCHED;
;             PG8_LDB(B0, 1, 0); PG8_LDB(B1, 1, 1); PG8_SCHED; PG8_LDA(At, 1, 0); PG8_STAGE(PG8_SA(0, 1), a2 + hstepA, voffA);
;             PG8_WAIT_V(8); PG8_WAIT_L(0); PG8_BAR; PG8_MMA(0, 0, At, B0); PG8_MMA(0, 1, At, B1); PG8_BAR; PG8_SCHED;
.LBB0_1010:
	s_add_u32 s14, s26, 0xfff80080
	s_addc_u32 s15, s27, -1
	s_add_i32 s41, 0, 0x10000
	s_cmp_eq_u32 s52, 28
	s_cselect_b32 s29, s1, s15
	s_cselect_b32 s28, s3, s14
	s_cselect_b32 s15, s7, s40
	s_cselect_b32 s14, s17, s19
	s_add_i32 s53, 0, 0x14000
	v_add_u32_e32 v142, s41, v1
	v_add_u32_e32 v158, s53, v1
	ds_read_b128 v[130:133], v142
	ds_read_b128 v[134:137], v142 offset:1024
	ds_read_b128 v[138:141], v142 offset:2048
	ds_read_b128 v[142:145], v142 offset:3072
	ds_read_b128 v[146:149], v158
	ds_read_b128 v[150:153], v158 offset:1024
	ds_read_b128 v[154:157], v158 offset:2048
	ds_read_b128 v[158:161], v158 offset:3072
	v_lshl_add_u64 v[178:179], s[26:27], 0, v[196:197]
	s_add_i32 m0, s25, 0xc000
	ds_read_b128 v[162:165], v181
	ds_read_b128 v[166:169], v181 offset:1024
	ds_read_b128 v[170:173], v181 offset:2048
	ds_read_b128 v[174:177], v181 offset:3072
	ds_read_b128 v[200:203], v181 offset:4096
	ds_read_b128 v[204:207], v181 offset:5120
	ds_read_b128 v[208:211], v181 offset:6144
	ds_read_b128 v[212:215], v181 offset:7168
	global_load_lds_dwordx4 v[178:179], off
	v_lshl_add_u64 v[178:179], s[26:27], 0, v[198:199]
	s_add_i32 m0, s25, 0xe000
	s_nop 0
	global_load_lds_dwordx4 v[178:179], off
	s_waitcnt vmcnt(8)
	s_waitcnt lgkmcnt(0)
	s_barrier
	s_setprio 1
	s_waitcnt lgkmcnt(0)
	v_mfma_f32_16x16x32_bf16 v[126:129], v[130:133], v[162:165], v[126:129]
	v_mfma_f32_16x16x32_bf16 v[122:125], v[138:141], v[162:165], v[122:125]
	v_mfma_f32_16x16x32_bf16 v[110:113], v[130:133], v[170:173], v[110:113]
	v_mfma_f32_16x16x32_bf16 v[106:109], v[138:141], v[170:173], v[106:109]
	v_mfma_f32_16x16x32_bf16 v[94:97], v[130:133], v[200:203], v[94:97]
	v_mfma_f32_16x16x32_bf16 v[90:93], v[138:141], v[200:203], v[90:93]
	v_mfma_f32_16x16x32_bf16 v[82:85], v[130:133], v[208:211], v[82:85]
	v_mfma_f32_16x16x32_bf16 v[74:77], v[138:141], v[208:211], v[74:77]
	v_mfma_f32_16x16x32_bf16 v[126:129], v[134:137], v[166:169], v[126:129]
	v_mfma_f32_16x16x32_bf16 v[122:125], v[142:145], v[166:169], v[122:125]
	v_mfma_f32_16x16x32_bf16 v[110:113], v[134:137], v[174:177], v[110:113]
	v_mfma_f32_16x16x32_bf16 v[106:109], v[142:145], v[174:177], v[106:109]
	v_mfma_f32_16x16x32_bf16 v[94:97], v[134:137], v[204:207], v[94:97]
	v_mfma_f32_16x16x32_bf16 v[90:93], v[142:145], v[204:207], v[90:93]
	v_mfma_f32_16x16x32_bf16 v[82:85], v[134:137], v[212:215], v[82:85]
	v_mfma_f32_16x16x32_bf16 v[74:77], v[142:145], v[212:215], v[74:77]
	s_setprio 0
	s_setprio 1
	v_mfma_f32_16x16x32_bf16 v[118:121], v[146:149], v[162:165], v[118:121]
	v_mfma_f32_16x16x32_bf16 v[114:117], v[154:157], v[162:165], v[114:117]
	v_mfma_f32_16x16x32_bf16 v[102:105], v[146:149], v[170:173], v[102:105]
	v_mfma_f32_16x16x32_bf16 v[98:101], v[154:157], v[170:173], v[98:101]
	v_mfma_f32_16x16x32_bf16 v[86:89], v[146:149], v[200:203], v[86:89]
	v_mfma_f32_16x16x32_bf16 v[78:81], v[154:157], v[200:203], v[78:81]
	v_mfma_f32_16x16x32_bf16 v[70:73], v[146:149], v[208:211], v[70:73]
	v_mfma_f32_16x16x32_bf16 v[66:69], v[154:157], v[208:211], v[66:69]
	v_mfma_f32_16x16x32_bf16 v[118:121], v[150:153], v[166:169], v[118:121]
	v_mfma_f32_16x16x32_bf16 v[114:117], v[158:161], v[166:169], v[114:117]
	v_mfma_f32_16x16x32_bf16 v[102:105], v[150:153], v[174:177], v[102:105]
	v_mfma_f32_16x16x32_bf16 v[98:101], v[158:161], v[174:177], v[98:101]
	v_mfma_f32_16x16x32_bf16 v[86:89], v[150:153], v[204:207], v[86:89]
	v_mfma_f32_16x16x32_bf16 v[78:81], v[158:161], v[204:207], v[78:81]
	v_mfma_f32_16x16x32_bf16 v[70:73], v[150:153], v[212:215], v[70:73]
	v_mfma_f32_16x16x32_bf16 v[66:69], v[158:161], v[212:215], v[66:69]
	s_setprio 0
	s_barrier
	s_add_i32 s41, s41, s30
	v_lshl_add_u64 v[178:179], s[14:15], 0, v[190:191]
	s_mov_b32 m0, s41
	ds_read_b128 v[162:165], v181 offset:16384
	ds_read_b128 v[166:169], v181 offset:17408
	ds_read_b128 v[170:173], v181 offset:18432
	ds_read_b128 v[174:177], v181 offset:19456
	ds_read_b128 v[200:203], v181 offset:20480
	ds_read_b128 v[204:207], v181 offset:21504
	ds_read_b128 v[208:211], v181 offset:22528
	ds_read_b128 v[212:215], v181 offset:23552
	global_load_lds_dwordx4 v[178:179], off
	s_add_i32 m0, s41, 0x2000
	s_add_u32 s62, s14, 0x80000
	v_lshl_add_u64 v[184:185], s[14:15], 0, v[194:195]
	s_addc_u32 s63, s15, 0
	s_add_i32 s41, s53, s30
	global_load_lds_dwordx4 v[184:185], off
	v_lshl_add_u64 v[216:217], s[62:63], 0, v[190:191]
	s_mov_b32 m0, s41
	v_lshl_add_u64 v[218:219], s[28:29], 0, v[192:193]
	global_load_lds_dwordx4 v[216:217], off
	v_lshl_add_u64 v[216:217], s[62:63], 0, v[194:195]
	s_add_i32 m0, s41, 0x2000
	s_nop 0
	global_load_lds_dwordx4 v[216:217], off
	v_lshl_add_u64 v[216:217], s[28:29], 0, v[188:189]
	s_mov_b32 m0, s25
	s_nop 0
	global_load_lds_dwordx4 v[216:217], off
	s_mov_b32 m0, s31
	s_nop 0
	global_load_lds_dwordx4 v[218:219], off
	s_waitcnt vmcnt(8)
	s_waitcnt lgkmcnt(0)
	s_barrier
; #define PG8_STAGE(bufoff, gbase, voff) do { _Pragma("unroll") for (int _i = 0; _i < 2; ++_i) \
;         __builtin_amdgcn_global_load_lds((const unsigned*)((const char*)(gbase) + (voff)[_i]), (LAS unsigned*)(lds + (bufoff) + ldsw + _i * 8192), 16, 0, 0); } while (0)
; #define PG8_LDA(dst, b, h) do { _Pragma("unroll") for (int m = 0; m < 4; ++m) _Pragma("unroll") for (int k = 0; k < 2; ++k) dst[m][k] = *(const LAS bf16x8*)(lds + PG8_SA(b, h) + aoff + m * 2048 + k * 1024); } while (0)
; #define PG8_LDB(dst, b, h) do { _Pragma("unroll") for (int n = 0; n < 2; ++n) _Pragma("unroll") for (int k = 0; k < 2; ++k) dst[n][k] = *(const LAS bf16x8*)(lds + PG8_SB(b, h) + boff + n * 2048 + k * 1024); } while (0)
; #define PG8_MMA(ai, bj, At, Bt) do { __builtin_amdgcn_s_setprio(1); _Pragma("unroll") for (int m = 0; m < 4; ++m) _Pragma("unroll") for (int n = 0; n < 2; ++n) _Pragma("unroll") for (int k = 0; k < 2; ++k) \
;         acc[ai][bj][m][n] = __builtin_amdgcn_mfma_f32_16x16x32_bf16(Bt[n][k], At[m][k], acc[ai][bj][m][n], 0, 0, 0); __builtin_amdgcn_s_setprio(0); } while (0)
; #define PG8_WAIT_V(n) asm volatile("s_waitcnt vmcnt(" #n ")" ::: "memory")
; #define PG8_WAIT_L(n) asm volatile("s_waitcnt lgkmcnt(" #n ")" ::: "memory")
; #define PG8_BAR __builtin_amdgcn_s_barrier()
; #define PG8_SCHED __builtin_amdgcn_sched_barrier(0)
; template <class Epi>
; __device__ __forceinline__ void gemm_phase(LAS unsigned char* lds, const Gemm g, const StaticOrder& S, const Epi& E) {
;     ...
;             PG8_WAIT_V(8); PG8_WAIT_L(0); PG8_BAR; PG8_MMA(1, 0, At, B0); PG8_MMA(1, 1, At, B1); PG8_BAR; PG8_SCHED;
;             PG8_LDB(B0, 1, 0); PG8_LDB(B1, 1, 1); PG8_SCHED; PG8_LDA(At, 1, 0); PG8_STAGE(PG8_SA(0, 1), a2 + hstepA, voffA);
;             PG8_WAIT_V(8); PG8_WAIT_L(0); PG8_BAR; PG8_MMA(0, 0, At, B0); PG8_MMA(0, 1, At, B1); PG8_BAR; PG8_SCHED;
;             PG8_LDA(At, 1, 1); PG8_STAGE(PG8_SB(1, 0), b3, voffB); PG8_STAGE(PG8_SB(1, 1), b3 + hstepB, voffB); PG8_STAGE(PG8_SA(1, 0), a3, voffA);
	s_setprio 1
	s_waitcnt lgkmcnt(0)
	v_mfma_f32_16x16x32_bf16 v[62:65], v[130:133], v[162:165], v[62:65]
	v_mfma_f32_16x16x32_bf16 v[58:61], v[138:141], v[162:165], v[58:61]
	v_mfma_f32_16x16x32_bf16 v[50:53], v[130:133], v[170:173], v[50:53]
	v_mfma_f32_16x16x32_bf16 v[42:45], v[138:141], v[170:173], v[42:45]
	v_mfma_f32_16x16x32_bf16 v[30:33], v[130:133], v[200:203], v[30:33]
	v_mfma_f32_16x16x32_bf16 v[26:29], v[138:141], v[200:203], v[26:29]
	v_mfma_f32_16x16x32_bf16 v[18:21], v[130:133], v[208:211], v[18:21]
	v_mfma_f32_16x16x32_bf16 v[10:13], v[138:141], v[208:211], v[10:13]
	v_mfma_f32_16x16x32_bf16 v[62:65], v[134:137], v[166:169], v[62:65]
	v_mfma_f32_16x16x32_bf16 v[58:61], v[142:145], v[166:169], v[58:61]
	v_mfma_f32_16x16x32_bf16 v[50:53], v[134:137], v[174:177], v[50:53]
	v_mfma_f32_16x16x32_bf16 v[42:45], v[142:145], v[174:177], v[42:45]
	v_mfma_f32_16x16x32_bf16 v[30:33], v[134:137], v[204:207], v[30:33]
	v_mfma_f32_16x16x32_bf16 v[26:29], v[142:145], v[204:207], v[26:29]
	v_mfma_f32_16x16x32_bf16 v[18:21], v[134:137], v[212:215], v[18:21]
	v_mfma_f32_16x16x32_bf16 v[10:13], v[142:145], v[212:215], v[10:13]
	s_setprio 0
	s_setprio 1
	v_mfma_f32_16x16x32_bf16 v[54:57], v[146:149], v[162:165], v[54:57]
	v_mfma_f32_16x16x32_bf16 v[46:49], v[154:157], v[162:165], v[46:49]
	v_mfma_f32_16x16x32_bf16 v[38:41], v[146:149], v[170:173], v[38:41]
	v_mfma_f32_16x16x32_bf16 v[34:37], v[154:157], v[170:173], v[34:37]
	v_mfma_f32_16x16x32_bf16 v[22:25], v[146:149], v[200:203], v[22:25]
	v_mfma_f32_16x16x32_bf16 v[14:17], v[154:157], v[200:203], v[14:17]
	v_mfma_f32_16x16x32_bf16 v[6:9], v[146:149], v[208:211], v[6:9]
	v_mfma_f32_16x16x32_bf16 v[2:5], v[154:157], v[208:211], v[2:5]
	v_mfma_f32_16x16x32_bf16 v[54:57], v[150:153], v[166:169], v[54:57]
	v_mfma_f32_16x16x32_bf16 v[46:49], v[158:161], v[166:169], v[46:49]
	v_mfma_f32_16x16x32_bf16 v[38:41], v[150:153], v[174:177], v[38:41]
	v_mfma_f32_16x16x32_bf16 v[34:37], v[158:161], v[174:177], v[34:37]
	v_mfma_f32_16x16x32_bf16 v[22:25], v[150:153], v[204:207], v[22:25]
	v_mfma_f32_16x16x32_bf16 v[14:17], v[158:161], v[204:207], v[14:17]
	v_mfma_f32_16x16x32_bf16 v[6:9], v[150:153], v[212:215], v[6:9]
	v_mfma_f32_16x16x32_bf16 v[2:5], v[158:161], v[212:215], v[2:5]
	s_setprio 0
	s_barrier
	s_add_i32 s41, 0, 0x18000
	s_add_i32 s53, 0, 0x1c000
	v_add_u32_e32 v142, s41, v1
	v_add_u32_e32 v158, s53, v1
	ds_read_b128 v[130:133], v142
	ds_read_b128 v[134:137], v142 offset:1024
	ds_read_b128 v[138:141], v142 offset:2048
	ds_read_b128 v[142:145], v142 offset:3072
	ds_read_b128 v[146:149], v158
	ds_read_b128 v[150:153], v158 offset:1024
	ds_read_b128 v[154:157], v158 offset:2048
	ds_read_b128 v[158:161], v158 offset:3072
	s_add_u32 s28, s28, 0x80000
	s_addc_u32 s29, s29, 0
	s_mov_b32 m0, s33
	v_lshl_add_u64 v[220:221], s[28:29], 0, v[188:189]
	ds_read_b128 v[162:165], v181 offset:32768
	ds_read_b128 v[166:169], v181 offset:33792
	ds_read_b128 v[170:173], v181 offset:34816
	ds_read_b128 v[174:177], v181 offset:35840
	ds_read_b128 v[200:203], v181 offset:36864
	ds_read_b128 v[204:207], v181 offset:37888
	ds_read_b128 v[208:211], v181 offset:38912
	ds_read_b128 v[212:215], v181 offset:39936
	global_load_lds_dwordx4 v[220:221], off
	v_lshl_add_u64 v[220:221], s[28:29], 0, v[192:193]
	s_mov_b32 m0, s34
	s_nop 0
	global_load_lds_dwordx4 v[220:221], off
	s_waitcnt vmcnt(8)
	s_waitcnt lgkmcnt(0)
	s_barrier
	s_setprio 1
	s_waitcnt lgkmcnt(0)
	v_mfma_f32_16x16x32_bf16 v[126:129], v[130:133], v[162:165], v[126:129]
	v_mfma_f32_16x16x32_bf16 v[122:125], v[138:141], v[162:165], v[122:125]
	v_mfma_f32_16x16x32_bf16 v[110:113], v[130:133], v[170:173], v[110:113]
	v_mfma_f32_16x16x32_bf16 v[106:109], v[138:141], v[170:173], v[106:109]
	v_mfma_f32_16x16x32_bf16 v[94:97], v[130:133], v[200:203], v[94:97]
	v_mfma_f32_16x16x32_bf16 v[90:93], v[138:141], v[200:203], v[90:93]
	v_mfma_f32_16x16x32_bf16 v[82:85], v[130:133], v[208:211], v[82:85]
	v_mfma_f32_16x16x32_bf16 v[74:77], v[138:141], v[208:211], v[74:77]
	v_mfma_f32_16x16x32_bf16 v[126:129], v[134:137], v[166:169], v[126:129]
	v_mfma_f32_16x16x32_bf16 v[122:125], v[142:145], v[166:169], v[122:125]
	v_mfma_f32_16x16x32_bf16 v[110:113], v[134:137], v[174:177], v[110:113]
	v_mfma_f32_16x16x32_bf16 v[106:109], v[142:145], v[174:177], v[106:109]
	v_mfma_f32_16x16x32_bf16 v[94:97], v[134:137], v[204:207], v[94:97]
	v_mfma_f32_16x16x32_bf16 v[90:93], v[142:145], v[204:207], v[90:93]
	v_mfma_f32_16x16x32_bf16 v[82:85], v[134:137], v[212:215], v[82:85]
	v_mfma_f32_16x16x32_bf16 v[74:77], v[142:145], v[212:215], v[74:77]
	s_setprio 0
	s_setprio 1
	v_mfma_f32_16x16x32_bf16 v[118:121], v[146:149], v[162:165], v[118:121]
	v_mfma_f32_16x16x32_bf16 v[114:117], v[154:157], v[162:165], v[114:117]
	v_mfma_f32_16x16x32_bf16 v[102:105], v[146:149], v[170:173], v[102:105]
	v_mfma_f32_16x16x32_bf16 v[98:101], v[154:157], v[170:173], v[98:101]
	v_mfma_f32_16x16x32_bf16 v[86:89], v[146:149], v[200:203], v[86:89]
	v_mfma_f32_16x16x32_bf16 v[78:81], v[154:157], v[200:203], v[78:81]
	v_mfma_f32_16x16x32_bf16 v[70:73], v[146:149], v[208:211], v[70:73]
	v_mfma_f32_16x16x32_bf16 v[66:69], v[154:157], v[208:211], v[66:69]
	v_mfma_f32_16x16x32_bf16 v[118:121], v[150:153], v[166:169], v[118:121]
	v_mfma_f32_16x16x32_bf16 v[114:117], v[158:161], v[166:169], v[114:117]
	v_mfma_f32_16x16x32_bf16 v[102:105], v[150:153], v[174:177], v[102:105]
	v_mfma_f32_16x16x32_bf16 v[98:101], v[158:161], v[174:177], v[98:101]
	v_mfma_f32_16x16x32_bf16 v[86:89], v[150:153], v[204:207], v[86:89]
	v_mfma_f32_16x16x32_bf16 v[78:81], v[158:161], v[204:207], v[78:81]
	v_mfma_f32_16x16x32_bf16 v[70:73], v[150:153], v[212:215], v[70:73]
	v_mfma_f32_16x16x32_bf16 v[66:69], v[158:161], v[212:215], v[66:69]
	s_setprio 0
	s_barrier
; #define PG8_STAGE(bufoff, gbase, voff) do { _Pragma("unroll") for (int _i = 0; _i < 2; ++_i) \
;         __builtin_amdgcn_global_load_lds((const unsigned*)((const char*)(gbase) + (voff)[_i]), (LAS unsigned*)(lds + (bufoff) + ldsw + _i * 8192), 16, 0, 0); } while (0)
; #define PG8_LDA(dst, b, h) do { _Pragma("unroll") for (int m = 0; m < 4; ++m) _Pragma("unroll") for (int k = 0; k < 2; ++k) dst[m][k] = *(const LAS bf16x8*)(lds + PG8_SA(b, h) + aoff + m * 2048 + k * 1024); } while (0)
; #define PG8_LDB(dst, b, h) do { _Pragma("unroll") for (int n = 0; n < 2; ++n) _Pragma("unroll") for (int k = 0; k < 2; ++k) dst[n][k] = *(const LAS bf16x8*)(lds + PG8_SB(b, h) + boff + n * 2048 + k * 1024); } while (0)
; #define PG8_MMA(ai, bj, At, Bt) do { __builtin_amdgcn_s_setprio(1); _Pragma("unroll") for (int m = 0; m < 4; ++m) _Pragma("unroll") for (int n = 0; n < 2; ++n) _Pragma("unroll") for (int k = 0; k < 2; ++k) \
;         acc[ai][bj][m][n] = __builtin_amdgcn_mfma_f32_16x16x32_bf16(Bt[n][k], At[m][k], acc[ai][bj][m][n], 0, 0, 0); __builtin_amdgcn_s_setprio(0); } while (0)
; #define PG8_WAIT_V(n) asm volatile("s_waitcnt vmcnt(" #n ")" ::: "memory")
; #define PG8_BAR __builtin_amdgcn_s_barrier()
; template <class Epi>
; __device__ __forceinline__ void gemm_phase(LAS unsigned char* lds, const Gemm g, const StaticOrder& S, const Epi& E) {
;     ...
;             PG8_LDB(B0, 0, 0); PG8_LDB(B1, 0, 1); PG8_SCHED; PG8_LDA(At, 0, 0); PG8_STAGE(PG8_SA(1, 1), a1 + hstepA, voffA);
;             PG8_WAIT_V(8); PG8_WAIT_L(0); PG8_BAR; PG8_MMA(0, 0, At, B0); PG8_MMA(0, 1, At, B1); PG8_BAR; PG8_SCHED;
;             PG8_LDA(At, 0, 1); PG8_STAGE(PG8_SB(0, 0), b2, voffB); PG8_STAGE(PG8_SB(0, 1), b2 + hstepB, voffB); PG8_STAGE(PG8_SA(0, 0), a2, voffA);
;             PG8_WAIT_V(8); PG8_WAIT_L(0); PG8_BAR; PG8_MMA(1, 0, At, B0); PG8_MMA(1, 1, At, B1); PG8_BAR; PG8_SCHED;
;             PG8_LDB(B0, 1, 0); PG8_LDB(B1, 1, 1); PG8_SCHED; PG8_LDA(At, 1, 0); PG8_STAGE(PG8_SA(0, 1), a2 + hstepA, voffA);
;             PG8_WAIT_V(8); PG8_WAIT_L(0); PG8_BAR; PG8_MMA(0, 0, At, B0); PG8_MMA(0, 1, At, B1); PG8_BAR; PG8_SCHED;
;             PG8_LDA(At, 1, 1); PG8_STAGE(PG8_SB(1, 0), b3, voffB); PG8_STAGE(PG8_SB(1, 1), b3 + hstepB, voffB); PG8_STAGE(PG8_SA(1, 0), a3, voffA);
;             PG8_WAIT_V(8); PG8_WAIT_L(0); PG8_BAR; PG8_MMA(1, 0, At, B0); PG8_MMA(1, 1, At, B1); PG8_BAR; PG8_SCHED;
;         }
	s_add_i32 s28, s41, s30
	v_lshl_add_u64 v[178:179], v[178:179], 0, s[84:85]
	s_mov_b32 m0, s28
	ds_read_b128 v[162:165], v181 offset:49152
	ds_read_b128 v[166:169], v181 offset:50176
	ds_read_b128 v[170:173], v181 offset:51200
	ds_read_b128 v[174:177], v181 offset:52224
	ds_read_b128 v[200:203], v181 offset:53248
	ds_read_b128 v[204:207], v181 offset:54272
	ds_read_b128 v[208:211], v181 offset:55296
	ds_read_b128 v[212:215], v181 offset:56320
	global_load_lds_dwordx4 v[178:179], off
	s_add_i32 m0, s28, 0x2000
	s_add_u32 s14, s14, 0x80080
	v_lshl_add_u64 v[178:179], v[184:185], 0, s[84:85]
	s_addc_u32 s15, s15, 0
	s_add_i32 s28, s53, s30
	global_load_lds_dwordx4 v[178:179], off
	v_lshl_add_u64 v[178:179], s[14:15], 0, v[190:191]
	s_mov_b32 m0, s28
	s_nop 0
	global_load_lds_dwordx4 v[178:179], off
	v_lshl_add_u64 v[178:179], s[14:15], 0, v[194:195]
	s_add_i32 m0, s28, 0x2000
	s_nop 0
	global_load_lds_dwordx4 v[178:179], off
	v_lshl_add_u64 v[178:179], v[216:217], 0, s[84:85]
	s_mov_b32 m0, s44
	s_nop 0
	global_load_lds_dwordx4 v[178:179], off
	v_lshl_add_u64 v[178:179], v[218:219], 0, s[84:85]
	s_mov_b32 m0, s45
	s_nop 0
	global_load_lds_dwordx4 v[178:179], off
	s_waitcnt vmcnt(8)
	s_waitcnt lgkmcnt(0)
	s_barrier
	s_setprio 1
	s_waitcnt lgkmcnt(0)
	v_mfma_f32_16x16x32_bf16 v[62:65], v[130:133], v[162:165], v[62:65]
	v_mfma_f32_16x16x32_bf16 v[58:61], v[138:141], v[162:165], v[58:61]
	v_mfma_f32_16x16x32_bf16 v[50:53], v[130:133], v[170:173], v[50:53]
	v_mfma_f32_16x16x32_bf16 v[42:45], v[138:141], v[170:173], v[42:45]
	v_mfma_f32_16x16x32_bf16 v[30:33], v[130:133], v[200:203], v[30:33]
	v_mfma_f32_16x16x32_bf16 v[26:29], v[138:141], v[200:203], v[26:29]
	v_mfma_f32_16x16x32_bf16 v[18:21], v[130:133], v[208:211], v[18:21]
	v_mfma_f32_16x16x32_bf16 v[10:13], v[138:141], v[208:211], v[10:13]
	v_mfma_f32_16x16x32_bf16 v[62:65], v[134:137], v[166:169], v[62:65]
	v_mfma_f32_16x16x32_bf16 v[58:61], v[142:145], v[166:169], v[58:61]
	v_mfma_f32_16x16x32_bf16 v[50:53], v[134:137], v[174:177], v[50:53]
	v_mfma_f32_16x16x32_bf16 v[42:45], v[142:145], v[174:177], v[42:45]
	v_mfma_f32_16x16x32_bf16 v[30:33], v[134:137], v[204:207], v[30:33]
	v_mfma_f32_16x16x32_bf16 v[26:29], v[142:145], v[204:207], v[26:29]
	v_mfma_f32_16x16x32_bf16 v[18:21], v[134:137], v[212:215], v[18:21]
	v_mfma_f32_16x16x32_bf16 v[10:13], v[142:145], v[212:215], v[10:13]
	s_setprio 0
	s_setprio 1
	v_mfma_f32_16x16x32_bf16 v[54:57], v[146:149], v[162:165], v[54:57]
	v_mfma_f32_16x16x32_bf16 v[46:49], v[154:157], v[162:165], v[46:49]
	v_mfma_f32_16x16x32_bf16 v[38:41], v[146:149], v[170:173], v[38:41]
	v_mfma_f32_16x16x32_bf16 v[34:37], v[154:157], v[170:173], v[34:37]
	v_mfma_f32_16x16x32_bf16 v[22:25], v[146:149], v[200:203], v[22:25]
	v_mfma_f32_16x16x32_bf16 v[14:17], v[154:157], v[200:203], v[14:17]
	v_mfma_f32_16x16x32_bf16 v[6:9], v[146:149], v[208:211], v[6:9]
	v_mfma_f32_16x16x32_bf16 v[2:5], v[154:157], v[208:211], v[2:5]
	v_mfma_f32_16x16x32_bf16 v[54:57], v[150:153], v[166:169], v[54:57]
	v_mfma_f32_16x16x32_bf16 v[46:49], v[158:161], v[166:169], v[46:49]
	v_mfma_f32_16x16x32_bf16 v[38:41], v[150:153], v[174:177], v[38:41]
	v_mfma_f32_16x16x32_bf16 v[34:37], v[158:161], v[174:177], v[34:37]
	v_mfma_f32_16x16x32_bf16 v[22:25], v[150:153], v[204:207], v[22:25]
	v_mfma_f32_16x16x32_bf16 v[14:17], v[158:161], v[204:207], v[14:17]
	v_mfma_f32_16x16x32_bf16 v[6:9], v[150:153], v[212:215], v[6:9]
	v_mfma_f32_16x16x32_bf16 v[2:5], v[158:161], v[212:215], v[2:5]
	s_setprio 0
	s_barrier
	s_add_i32 s52, s52, 2
	s_add_u32 s26, s26, 0x100
	s_addc_u32 s27, s27, 0
	s_add_u32 s19, s19, 0x100
	s_addc_u32 s40, s40, 0
	s_cmp_gt_u32 s52, 29
	s_cbranch_scc0 .LBB0_1010
	s_cmp_ge_u32 s74, 32
	s_cbranch_scc1 .Lwpf_a
	s_lshl_b32 s100, s74, 9
	v_add_u32_e32 v130, s100, v246
	v_lshrrev_b32_e32 v131, 3, v130
	v_and_b32_e32 v130, 7, v130
	v_lshlrev_b32_e32 v130, 7, v130
	v_lshl_add_u32 v130, v131, 12, v130
	s_add_u32 s100, s88, 0x1800000
	s_addc_u32 s101, s89, 0
	s_mov_b32 m0, 0x21000
	s_nop 0
	global_load_lds_dword v130, s[100:101]

;     __device__ void init(int M, int N, int G_, int c_) { nM = M / BM; nN = N / BM; nwg = nM * nN; G = launder_s(G_); c = launder_s(c_); }
; #define GRID_BAR() do { XcdBarrier b_; b_.bar = (unsigned*)(args.ws + WS_CTL); b_.x = xb_xcc_id(); b_.st = (volatile LAS unsigned*)(lds + LDS_BYTES - 64); xcd_barrier(b_); } while (0)
; #define GRID_BAR() grid.sync()
; __global__ void __launch_bounds__(NTHR, 2) mk_fwd(Args args) {
;     ...
;             s5_scan1(lds, SP, U, ES, bid, G);
;             GRID_BAR();
;             s5_scan2(lds, SP, U, ES, Gb, bid, G);
;             GRID_BAR();
;             { pg8::Gemm g{Gb, (const bf16_t*)(wm + WM_C_GLU), T, 2 * D, D, D, D, 0, 0}; pg8::StaticOrder S; S.init(T, 2 * D, G, bid); pg8::EpiGlu E{out, HB0, SSQ0, PTAB}; pg8::gemm_phase(lds, g, S, E); }
.LBB0_1168:
	s_or_b64 exec, exec, s[4:5]
	s_waitcnt lgkmcnt(0)
	v_mov_b32_e32 v2, v246
	s_barrier
	s_cmp_ge_u32 s74, 32
	s_cbranch_scc1 .Lwpf_j
	s_lshl_b32 s100, s74, 9
	v_add_u32_e32 v100, s100, v246
	v_lshrrev_b32_e32 v101, 3, v100
	v_and_b32_e32 v100, 7, v100
	v_lshlrev_b32_e32 v100, 7, v100
	v_lshl_add_u32 v100, v101, 12, v100
	s_add_u32 s100, s38, 0x15900000
	s_addc_u32 s101, s39, 0
	s_mov_b32 m0, 0x21000
	s_nop 0
	global_load_lds_dword v100, s[100:101]

; #define PG8_STAGE(bufoff, gbase, voff) do { _Pragma("unroll") for (int _i = 0; _i < 2; ++_i) \
;         __builtin_amdgcn_global_load_lds((const unsigned*)((const char*)(gbase) + (voff)[_i]), (LAS unsigned*)(lds + (bufoff) + ldsw + _i * 8192), 16, 0, 0); } while (0)
; #define PG8_LDA(dst, b, h) do { _Pragma("unroll") for (int m = 0; m < 4; ++m) _Pragma("unroll") for (int k = 0; k < 2; ++k) dst[m][k] = *(const LAS bf16x8*)(lds + PG8_SA(b, h) + aoff + m * 2048 + k * 1024); } while (0)
; #define PG8_LDB(dst, b, h) do { _Pragma("unroll") for (int n = 0; n < 2; ++n) _Pragma("unroll") for (int k = 0; k < 2; ++k) dst[n][k] = *(const LAS bf16x8*)(lds + PG8_SB(b, h) + boff + n * 2048 + k * 1024); } while (0)
; #define PG8_MMA(ai, bj, At, Bt) do { __builtin_amdgcn_s_setprio(1); _Pragma("unroll") for (int m = 0; m < 4; ++m) _Pragma("unroll") for (int n = 0; n < 2; ++n) _Pragma("unroll") for (int k = 0; k < 2; ++k) \
;         acc[ai][bj][m][n] = __builtin_amdgcn_mfma_f32_16x16x32_bf16(Bt[n][k], At[m][k], acc[ai][bj][m][n], 0, 0, 0); __builtin_amdgcn_s_setprio(0); } while (0)
; #define PG8_WAIT_V(n) asm volatile("s_waitcnt vmcnt(" #n ")" ::: "memory")
; #define PG8_WAIT_L(n) asm volatile("s_waitcnt lgkmcnt(" #n ")" ::: "memory")
; #define PG8_BAR __builtin_amdgcn_s_barrier()
; #define PG8_SCHED __builtin_amdgcn_sched_barrier(0)
; template <class Epi>
; __device__ __forceinline__ void gemm_phase(LAS unsigned char* lds, const Gemm g, const StaticOrder& S, const Epi& E) {
;     ...
;             PG8_LDB(B0, 0, 0); PG8_LDB(B1, 0, 1); PG8_SCHED; PG8_LDA(At, 0, 0); PG8_STAGE(PG8_SA(1, 1), a1 + hstepA, voffA);
;             PG8_WAIT_V(8); PG8_WAIT_L(0); PG8_BAR; PG8_MMA(0, 0, At, B0); PG8_MMA(0, 1, At, B1); PG8_BAR; PG8_SCHED;
;             PG8_LDA(At, 0, 1); PG8_STAGE(PG8_SB(0, 0), b2, voffB); PG8_STAGE(PG8_SB(0, 1), b2 + hstepB, voffB); PG8_STAGE(PG8_SA(0, 0), a2, voffA);
;             PG8_WAIT_V(8); PG8_WAIT_L(0); PG8_BAR; PG8_MMA(1, 0, At, B0); PG8_MMA(1, 1, At, B1); PG8_BAR; PG8_SCHED;
;             PG8_LDB(B0, 1, 0); PG8_LDB(B1, 1, 1); PG8_SCHED; PG8_LDA(At, 1, 0); PG8_STAGE(PG8_SA(0, 1), a2 + hstepA, voffA);
;             PG8_WAIT_V(8); PG8_WAIT_L(0); PG8_BAR; PG8_MMA(0, 0, At, B0); PG8_MMA(0, 1, At, B1); PG8_BAR; PG8_SCHED;
.LBB0_1324:
	s_add_u32 s14, s24, 0xfff80080
	s_addc_u32 s15, s25, -1
	s_add_i32 s53, 0, 0x10000
	s_cmp_eq_u32 s41, 28
	s_cselect_b32 s27, s3, s15
	s_cselect_b32 s26, s7, s14
	s_cselect_b32 s15, s13, s52
	s_cselect_b32 s14, s17, s40
	s_add_i32 s69, 0, 0x14000
	v_add_u32_e32 v142, s53, v1
	v_add_u32_e32 v158, s69, v1
	ds_read_b128 v[130:133], v142
	ds_read_b128 v[134:137], v142 offset:1024
	ds_read_b128 v[138:141], v142 offset:2048
	ds_read_b128 v[142:145], v142 offset:3072
	ds_read_b128 v[146:149], v158
	ds_read_b128 v[150:153], v158 offset:1024
	ds_read_b128 v[154:157], v158 offset:2048
	ds_read_b128 v[158:161], v158 offset:3072
	v_lshl_add_u64 v[178:179], s[24:25], 0, v[170:171]
	s_add_i32 m0, s23, 0xc000
	ds_read_b128 v[162:165], v181
	ds_read_b128 v[174:177], v181 offset:1024
	ds_read_b128 v[188:191], v181 offset:2048
	ds_read_b128 v[192:195], v181 offset:3072
	ds_read_b128 v[196:199], v181 offset:4096
	ds_read_b128 v[200:203], v181 offset:5120
	ds_read_b128 v[204:207], v181 offset:6144
	ds_read_b128 v[208:211], v181 offset:7168
	global_load_lds_dwordx4 v[178:179], off
	v_lshl_add_u64 v[178:179], s[24:25], 0, v[172:173]
	s_add_i32 m0, s23, 0xe000
	s_nop 0
	global_load_lds_dwordx4 v[178:179], off
	s_waitcnt vmcnt(8)
	s_waitcnt lgkmcnt(0)
	s_barrier
	s_setprio 1
	s_waitcnt lgkmcnt(0)
	v_mfma_f32_16x16x32_bf16 v[122:125], v[130:133], v[162:165], v[122:125]
	v_mfma_f32_16x16x32_bf16 v[118:121], v[138:141], v[162:165], v[118:121]
	v_mfma_f32_16x16x32_bf16 v[110:113], v[130:133], v[188:191], v[110:113]
	v_mfma_f32_16x16x32_bf16 v[102:105], v[138:141], v[188:191], v[102:105]
	v_mfma_f32_16x16x32_bf16 v[94:97], v[130:133], v[196:199], v[94:97]
	v_mfma_f32_16x16x32_bf16 v[86:89], v[138:141], v[196:199], v[86:89]
	v_mfma_f32_16x16x32_bf16 v[78:81], v[130:133], v[204:207], v[78:81]
	v_mfma_f32_16x16x32_bf16 v[70:73], v[138:141], v[204:207], v[70:73]
	v_mfma_f32_16x16x32_bf16 v[122:125], v[134:137], v[174:177], v[122:125]
	v_mfma_f32_16x16x32_bf16 v[118:121], v[142:145], v[174:177], v[118:121]
	v_mfma_f32_16x16x32_bf16 v[110:113], v[134:137], v[192:195], v[110:113]
	v_mfma_f32_16x16x32_bf16 v[102:105], v[142:145], v[192:195], v[102:105]
	v_mfma_f32_16x16x32_bf16 v[94:97], v[134:137], v[200:203], v[94:97]
	v_mfma_f32_16x16x32_bf16 v[86:89], v[142:145], v[200:203], v[86:89]
	v_mfma_f32_16x16x32_bf16 v[78:81], v[134:137], v[208:211], v[78:81]
	v_mfma_f32_16x16x32_bf16 v[70:73], v[142:145], v[208:211], v[70:73]
	s_setprio 0
	s_setprio 1
	v_mfma_f32_16x16x32_bf16 v[126:129], v[146:149], v[162:165], v[126:129]
	v_mfma_f32_16x16x32_bf16 v[114:117], v[154:157], v[162:165], v[114:117]
	v_mfma_f32_16x16x32_bf16 v[106:109], v[146:149], v[188:191], v[106:109]
	v_mfma_f32_16x16x32_bf16 v[98:101], v[154:157], v[188:191], v[98:101]
	v_mfma_f32_16x16x32_bf16 v[90:93], v[146:149], v[196:199], v[90:93]
	v_mfma_f32_16x16x32_bf16 v[82:85], v[154:157], v[196:199], v[82:85]
	v_mfma_f32_16x16x32_bf16 v[74:77], v[146:149], v[204:207], v[74:77]
	v_mfma_f32_16x16x32_bf16 v[66:69], v[154:157], v[204:207], v[66:69]
	v_mfma_f32_16x16x32_bf16 v[126:129], v[150:153], v[174:177], v[126:129]
	v_mfma_f32_16x16x32_bf16 v[114:117], v[158:161], v[174:177], v[114:117]
	v_mfma_f32_16x16x32_bf16 v[106:109], v[150:153], v[192:195], v[106:109]
	v_mfma_f32_16x16x32_bf16 v[98:101], v[158:161], v[192:195], v[98:101]
	v_mfma_f32_16x16x32_bf16 v[90:93], v[150:153], v[200:203], v[90:93]
	v_mfma_f32_16x16x32_bf16 v[82:85], v[158:161], v[200:203], v[82:85]
	v_mfma_f32_16x16x32_bf16 v[74:77], v[150:153], v[208:211], v[74:77]
	v_mfma_f32_16x16x32_bf16 v[66:69], v[158:161], v[208:211], v[66:69]
	s_setprio 0
	s_barrier
	s_add_i32 s53, s53, s28
	v_lshl_add_u64 v[178:179], s[14:15], 0, v[166:167]
	s_mov_b32 m0, s53
	ds_read_b128 v[162:165], v181 offset:16384
	ds_read_b128 v[174:177], v181 offset:17408
	ds_read_b128 v[188:191], v181 offset:18432
	ds_read_b128 v[192:195], v181 offset:19456
	ds_read_b128 v[196:199], v181 offset:20480
	ds_read_b128 v[200:203], v181 offset:21504
	ds_read_b128 v[204:207], v181 offset:22528
	ds_read_b128 v[208:211], v181 offset:23552
	global_load_lds_dwordx4 v[178:179], off
	s_add_i32 m0, s53, 0x2000
	s_add_u32 s64, s14, 0x80000
	v_lshl_add_u64 v[184:185], s[14:15], 0, v[168:169]
	s_addc_u32 s65, s15, 0
	s_add_i32 s53, s69, s28
	global_load_lds_dwordx4 v[184:185], off
	v_lshl_add_u64 v[212:213], s[64:65], 0, v[166:167]
	s_mov_b32 m0, s53
	v_lshl_add_u64 v[214:215], s[26:27], 0, v[168:169]
	global_load_lds_dwordx4 v[212:213], off
	v_lshl_add_u64 v[212:213], s[64:65], 0, v[168:169]
	s_add_i32 m0, s53, 0x2000
	s_nop 0
	global_load_lds_dwordx4 v[212:213], off
	v_lshl_add_u64 v[212:213], s[26:27], 0, v[166:167]
	s_mov_b32 m0, s23
	s_nop 0
	global_load_lds_dwordx4 v[212:213], off
	s_mov_b32 m0, s29
	s_nop 0
	global_load_lds_dwordx4 v[214:215], off
	s_waitcnt vmcnt(8)
	s_waitcnt lgkmcnt(0)
	s_barrier
; #define PG8_STAGE(bufoff, gbase, voff) do { _Pragma("unroll") for (int _i = 0; _i < 2; ++_i) \
;         __builtin_amdgcn_global_load_lds((const unsigned*)((const char*)(gbase) + (voff)[_i]), (LAS unsigned*)(lds + (bufoff) + ldsw + _i * 8192), 16, 0, 0); } while (0)
; #define PG8_LDA(dst, b, h) do { _Pragma("unroll") for (int m = 0; m < 4; ++m) _Pragma("unroll") for (int k = 0; k < 2; ++k) dst[m][k] = *(const LAS bf16x8*)(lds + PG8_SA(b, h) + aoff + m * 2048 + k * 1024); } while (0)
; #define PG8_LDB(dst, b, h) do { _Pragma("unroll") for (int n = 0; n < 2; ++n) _Pragma("unroll") for (int k = 0; k < 2; ++k) dst[n][k] = *(const LAS bf16x8*)(lds + PG8_SB(b, h) + boff + n * 2048 + k * 1024); } while (0)
; #define PG8_MMA(ai, bj, At, Bt) do { __builtin_amdgcn_s_setprio(1); _Pragma("unroll") for (int m = 0; m < 4; ++m) _Pragma("unroll") for (int n = 0; n < 2; ++n) _Pragma("unroll") for (int k = 0; k < 2; ++k) \
;         acc[ai][bj][m][n] = __builtin_amdgcn_mfma_f32_16x16x32_bf16(Bt[n][k], At[m][k], acc[ai][bj][m][n], 0, 0, 0); __builtin_amdgcn_s_setprio(0); } while (0)
; #define PG8_WAIT_V(n) asm volatile("s_waitcnt vmcnt(" #n ")" ::: "memory")
; #define PG8_WAIT_L(n) asm volatile("s_waitcnt lgkmcnt(" #n ")" ::: "memory")
; #define PG8_BAR __builtin_amdgcn_s_barrier()
; #define PG8_SCHED __builtin_amdgcn_sched_barrier(0)
; template <class Epi>
; __device__ __forceinline__ void gemm_phase(LAS unsigned char* lds, const Gemm g, const StaticOrder& S, const Epi& E) {
;     ...
;             PG8_WAIT_V(8); PG8_WAIT_L(0); PG8_BAR; PG8_MMA(1, 0, At, B0); PG8_MMA(1, 1, At, B1); PG8_BAR; PG8_SCHED;
;             PG8_LDB(B0, 1, 0); PG8_LDB(B1, 1, 1); PG8_SCHED; PG8_LDA(At, 1, 0); PG8_STAGE(PG8_SA(0, 1), a2 + hstepA, voffA);
;             PG8_WAIT_V(8); PG8_WAIT_L(0); PG8_BAR; PG8_MMA(0, 0, At, B0); PG8_MMA(0, 1, At, B1); PG8_BAR; PG8_SCHED;
;             PG8_LDA(At, 1, 1); PG8_STAGE(PG8_SB(1, 0), b3, voffB); PG8_STAGE(PG8_SB(1, 1), b3 + hstepB, voffB); PG8_STAGE(PG8_SA(1, 0), a3, voffA);
	s_setprio 1
	s_waitcnt lgkmcnt(0)
	v_mfma_f32_16x16x32_bf16 v[62:65], v[130:133], v[162:165], v[62:65]
	v_mfma_f32_16x16x32_bf16 v[54:57], v[138:141], v[162:165], v[54:57]
	v_mfma_f32_16x16x32_bf16 v[46:49], v[130:133], v[188:191], v[46:49]
	v_mfma_f32_16x16x32_bf16 v[38:41], v[138:141], v[188:191], v[38:41]
	v_mfma_f32_16x16x32_bf16 v[30:33], v[130:133], v[196:199], v[30:33]
	v_mfma_f32_16x16x32_bf16 v[22:25], v[138:141], v[196:199], v[22:25]
	v_mfma_f32_16x16x32_bf16 v[14:17], v[130:133], v[204:207], v[14:17]
	v_mfma_f32_16x16x32_bf16 v[6:9], v[138:141], v[204:207], v[6:9]
	v_mfma_f32_16x16x32_bf16 v[62:65], v[134:137], v[174:177], v[62:65]
	v_mfma_f32_16x16x32_bf16 v[54:57], v[142:145], v[174:177], v[54:57]
	v_mfma_f32_16x16x32_bf16 v[46:49], v[134:137], v[192:195], v[46:49]
	v_mfma_f32_16x16x32_bf16 v[38:41], v[142:145], v[192:195], v[38:41]
	v_mfma_f32_16x16x32_bf16 v[30:33], v[134:137], v[200:203], v[30:33]
	v_mfma_f32_16x16x32_bf16 v[22:25], v[142:145], v[200:203], v[22:25]
	v_mfma_f32_16x16x32_bf16 v[14:17], v[134:137], v[208:211], v[14:17]
	v_mfma_f32_16x16x32_bf16 v[6:9], v[142:145], v[208:211], v[6:9]
	s_setprio 0
	s_setprio 1
	v_mfma_f32_16x16x32_bf16 v[58:61], v[146:149], v[162:165], v[58:61]
	v_mfma_f32_16x16x32_bf16 v[50:53], v[154:157], v[162:165], v[50:53]
	v_mfma_f32_16x16x32_bf16 v[42:45], v[146:149], v[188:191], v[42:45]
	v_mfma_f32_16x16x32_bf16 v[34:37], v[154:157], v[188:191], v[34:37]
	v_mfma_f32_16x16x32_bf16 v[26:29], v[146:149], v[196:199], v[26:29]
	v_mfma_f32_16x16x32_bf16 v[18:21], v[154:157], v[196:199], v[18:21]
	v_mfma_f32_16x16x32_bf16 v[10:13], v[146:149], v[204:207], v[10:13]
	v_mfma_f32_16x16x32_bf16 v[2:5], v[154:157], v[204:207], v[2:5]
	v_mfma_f32_16x16x32_bf16 v[58:61], v[150:153], v[174:177], v[58:61]
	v_mfma_f32_16x16x32_bf16 v[50:53], v[158:161], v[174:177], v[50:53]
	v_mfma_f32_16x16x32_bf16 v[42:45], v[150:153], v[192:195], v[42:45]
	v_mfma_f32_16x16x32_bf16 v[34:37], v[158:161], v[192:195], v[34:37]
	v_mfma_f32_16x16x32_bf16 v[26:29], v[150:153], v[200:203], v[26:29]
	v_mfma_f32_16x16x32_bf16 v[18:21], v[158:161], v[200:203], v[18:21]
	v_mfma_f32_16x16x32_bf16 v[10:13], v[150:153], v[208:211], v[10:13]
	v_mfma_f32_16x16x32_bf16 v[2:5], v[158:161], v[208:211], v[2:5]
	s_setprio 0
	s_barrier
	s_add_i32 s53, 0, 0x18000
	s_add_i32 s64, 0, 0x1c000
	v_add_u32_e32 v142, s53, v1
	v_add_u32_e32 v158, s64, v1
	ds_read_b128 v[130:133], v142
	ds_read_b128 v[134:137], v142 offset:1024
	ds_read_b128 v[138:141], v142 offset:2048
	ds_read_b128 v[142:145], v142 offset:3072
	ds_read_b128 v[146:149], v158
	ds_read_b128 v[150:153], v158 offset:1024
	ds_read_b128 v[154:157], v158 offset:2048
	ds_read_b128 v[158:161], v158 offset:3072
	s_add_u32 s26, s26, 0x80000
	s_addc_u32 s27, s27, 0
	s_mov_b32 m0, s30
	v_lshl_add_u64 v[216:217], s[26:27], 0, v[166:167]
	ds_read_b128 v[162:165], v181 offset:32768
	ds_read_b128 v[174:177], v181 offset:33792
	ds_read_b128 v[188:191], v181 offset:34816
	ds_read_b128 v[192:195], v181 offset:35840
	ds_read_b128 v[196:199], v181 offset:36864
	ds_read_b128 v[200:203], v181 offset:37888
	ds_read_b128 v[204:207], v181 offset:38912
	ds_read_b128 v[208:211], v181 offset:39936
	global_load_lds_dwordx4 v[216:217], off
	v_lshl_add_u64 v[216:217], s[26:27], 0, v[168:169]
	s_mov_b32 m0, s31
	s_nop 0
	global_load_lds_dwordx4 v[216:217], off
	s_waitcnt vmcnt(8)
	s_waitcnt lgkmcnt(0)
	s_barrier
	s_setprio 1
	s_waitcnt lgkmcnt(0)
	v_mfma_f32_16x16x32_bf16 v[122:125], v[130:133], v[162:165], v[122:125]
	v_mfma_f32_16x16x32_bf16 v[118:121], v[138:141], v[162:165], v[118:121]
	v_mfma_f32_16x16x32_bf16 v[110:113], v[130:133], v[188:191], v[110:113]
	v_mfma_f32_16x16x32_bf16 v[102:105], v[138:141], v[188:191], v[102:105]
	v_mfma_f32_16x16x32_bf16 v[94:97], v[130:133], v[196:199], v[94:97]
	v_mfma_f32_16x16x32_bf16 v[86:89], v[138:141], v[196:199], v[86:89]
	v_mfma_f32_16x16x32_bf16 v[78:81], v[130:133], v[204:207], v[78:81]
	v_mfma_f32_16x16x32_bf16 v[70:73], v[138:141], v[204:207], v[70:73]
	v_mfma_f32_16x16x32_bf16 v[122:125], v[134:137], v[174:177], v[122:125]
	v_mfma_f32_16x16x32_bf16 v[118:121], v[142:145], v[174:177], v[118:121]
	v_mfma_f32_16x16x32_bf16 v[110:113], v[134:137], v[192:195], v[110:113]
	v_mfma_f32_16x16x32_bf16 v[102:105], v[142:145], v[192:195], v[102:105]
	v_mfma_f32_16x16x32_bf16 v[94:97], v[134:137], v[200:203], v[94:97]
	v_mfma_f32_16x16x32_bf16 v[86:89], v[142:145], v[200:203], v[86:89]
	v_mfma_f32_16x16x32_bf16 v[78:81], v[134:137], v[208:211], v[78:81]
	v_mfma_f32_16x16x32_bf16 v[70:73], v[142:145], v[208:211], v[70:73]
	s_setprio 0
	s_setprio 1
	v_mfma_f32_16x16x32_bf16 v[126:129], v[146:149], v[162:165], v[126:129]
	v_mfma_f32_16x16x32_bf16 v[114:117], v[154:157], v[162:165], v[114:117]
	v_mfma_f32_16x16x32_bf16 v[106:109], v[146:149], v[188:191], v[106:109]
	v_mfma_f32_16x16x32_bf16 v[98:101], v[154:157], v[188:191], v[98:101]
	v_mfma_f32_16x16x32_bf16 v[90:93], v[146:149], v[196:199], v[90:93]
	v_mfma_f32_16x16x32_bf16 v[82:85], v[154:157], v[196:199], v[82:85]
	v_mfma_f32_16x16x32_bf16 v[74:77], v[146:149], v[204:207], v[74:77]
	v_mfma_f32_16x16x32_bf16 v[66:69], v[154:157], v[204:207], v[66:69]
	v_mfma_f32_16x16x32_bf16 v[126:129], v[150:153], v[174:177], v[126:129]
	v_mfma_f32_16x16x32_bf16 v[114:117], v[158:161], v[174:177], v[114:117]
	v_mfma_f32_16x16x32_bf16 v[106:109], v[150:153], v[192:195], v[106:109]
	v_mfma_f32_16x16x32_bf16 v[98:101], v[158:161], v[192:195], v[98:101]
	v_mfma_f32_16x16x32_bf16 v[90:93], v[150:153], v[200:203], v[90:93]
	v_mfma_f32_16x16x32_bf16 v[82:85], v[158:161], v[200:203], v[82:85]
	v_mfma_f32_16x16x32_bf16 v[74:77], v[150:153], v[208:211], v[74:77]
	v_mfma_f32_16x16x32_bf16 v[66:69], v[158:161], v[208:211], v[66:69]
	s_setprio 0
	s_barrier
; #define PG8_STAGE(bufoff, gbase, voff) do { _Pragma("unroll") for (int _i = 0; _i < 2; ++_i) \
;         __builtin_amdgcn_global_load_lds((const unsigned*)((const char*)(gbase) + (voff)[_i]), (LAS unsigned*)(lds + (bufoff) + ldsw + _i * 8192), 16, 0, 0); } while (0)
; #define PG8_LDA(dst, b, h) do { _Pragma("unroll") for (int m = 0; m < 4; ++m) _Pragma("unroll") for (int k = 0; k < 2; ++k) dst[m][k] = *(const LAS bf16x8*)(lds + PG8_SA(b, h) + aoff + m * 2048 + k * 1024); } while (0)
; #define PG8_LDB(dst, b, h) do { _Pragma("unroll") for (int n = 0; n < 2; ++n) _Pragma("unroll") for (int k = 0; k < 2; ++k) dst[n][k] = *(const LAS bf16x8*)(lds + PG8_SB(b, h) + boff + n * 2048 + k * 1024); } while (0)
; #define PG8_MMA(ai, bj, At, Bt) do { __builtin_amdgcn_s_setprio(1); _Pragma("unroll") for (int m = 0; m < 4; ++m) _Pragma("unroll") for (int n = 0; n < 2; ++n) _Pragma("unroll") for (int k = 0; k < 2; ++k) \
;         acc[ai][bj][m][n] = __builtin_amdgcn_mfma_f32_16x16x32_bf16(Bt[n][k], At[m][k], acc[ai][bj][m][n], 0, 0, 0); __builtin_amdgcn_s_setprio(0); } while (0)
; #define PG8_WAIT_V(n) asm volatile("s_waitcnt vmcnt(" #n ")" ::: "memory")
; #define PG8_BAR __builtin_amdgcn_s_barrier()
; template <class Epi>
; __device__ __forceinline__ void gemm_phase(LAS unsigned char* lds, const Gemm g, const StaticOrder& S, const Epi& E) {
;     ...
;             PG8_LDB(B0, 0, 0); PG8_LDB(B1, 0, 1); PG8_SCHED; PG8_LDA(At, 0, 0); PG8_STAGE(PG8_SA(1, 1), a1 + hstepA, voffA);
;             PG8_WAIT_V(8); PG8_WAIT_L(0); PG8_BAR; PG8_MMA(0, 0, At, B0); PG8_MMA(0, 1, At, B1); PG8_BAR; PG8_SCHED;
;             PG8_LDA(At, 0, 1); PG8_STAGE(PG8_SB(0, 0), b2, voffB); PG8_STAGE(PG8_SB(0, 1), b2 + hstepB, voffB); PG8_STAGE(PG8_SA(0, 0), a2, voffA);
;             PG8_WAIT_V(8); PG8_WAIT_L(0); PG8_BAR; PG8_MMA(1, 0, At, B0); PG8_MMA(1, 1, At, B1); PG8_BAR; PG8_SCHED;
;             PG8_LDB(B0, 1, 0); PG8_LDB(B1, 1, 1); PG8_SCHED; PG8_LDA(At, 1, 0); PG8_STAGE(PG8_SA(0, 1), a2 + hstepA, voffA);
;             PG8_WAIT_V(8); PG8_WAIT_L(0); PG8_BAR; PG8_MMA(0, 0, At, B0); PG8_MMA(0, 1, At, B1); PG8_BAR; PG8_SCHED;
;             PG8_LDA(At, 1, 1); PG8_STAGE(PG8_SB(1, 0), b3, voffB); PG8_STAGE(PG8_SB(1, 1), b3 + hstepB, voffB); PG8_STAGE(PG8_SA(1, 0), a3, voffA);
;             PG8_WAIT_V(8); PG8_WAIT_L(0); PG8_BAR; PG8_MMA(1, 0, At, B0); PG8_MMA(1, 1, At, B1); PG8_BAR; PG8_SCHED;
;         }
	s_add_i32 s26, s53, s28
	v_lshl_add_u64 v[178:179], v[178:179], 0, s[84:85]
	s_mov_b32 m0, s26
	ds_read_b128 v[162:165], v181 offset:49152
	ds_read_b128 v[174:177], v181 offset:50176
	ds_read_b128 v[188:191], v181 offset:51200
	ds_read_b128 v[192:195], v181 offset:52224
	ds_read_b128 v[196:199], v181 offset:53248
	ds_read_b128 v[200:203], v181 offset:54272
	ds_read_b128 v[204:207], v181 offset:55296
	ds_read_b128 v[208:211], v181 offset:56320
	global_load_lds_dwordx4 v[178:179], off
	s_add_i32 m0, s26, 0x2000
	s_add_u32 s14, s14, 0x80080
	v_lshl_add_u64 v[178:179], v[184:185], 0, s[84:85]
	s_addc_u32 s15, s15, 0
	s_add_i32 s26, s64, s28
	global_load_lds_dwordx4 v[178:179], off
	v_lshl_add_u64 v[178:179], s[14:15], 0, v[166:167]
	s_mov_b32 m0, s26
	s_nop 0
	global_load_lds_dwordx4 v[178:179], off
	v_lshl_add_u64 v[178:179], s[14:15], 0, v[168:169]
	s_add_i32 m0, s26, 0x2000
	s_nop 0
	global_load_lds_dwordx4 v[178:179], off
	v_lshl_add_u64 v[178:179], v[212:213], 0, s[84:85]
	s_mov_b32 m0, s35
	s_nop 0
	global_load_lds_dwordx4 v[178:179], off
	v_lshl_add_u64 v[178:179], v[214:215], 0, s[84:85]
	s_mov_b32 m0, s42
	s_nop 0
	global_load_lds_dwordx4 v[178:179], off
	s_waitcnt vmcnt(8)
	s_waitcnt lgkmcnt(0)
	s_barrier
	s_setprio 1
	s_waitcnt lgkmcnt(0)
	v_mfma_f32_16x16x32_bf16 v[62:65], v[130:133], v[162:165], v[62:65]
	v_mfma_f32_16x16x32_bf16 v[54:57], v[138:141], v[162:165], v[54:57]
	v_mfma_f32_16x16x32_bf16 v[46:49], v[130:133], v[188:191], v[46:49]
	v_mfma_f32_16x16x32_bf16 v[38:41], v[138:141], v[188:191], v[38:41]
	v_mfma_f32_16x16x32_bf16 v[30:33], v[130:133], v[196:199], v[30:33]
	v_mfma_f32_16x16x32_bf16 v[22:25], v[138:141], v[196:199], v[22:25]
	v_mfma_f32_16x16x32_bf16 v[14:17], v[130:133], v[204:207], v[14:17]
	v_mfma_f32_16x16x32_bf16 v[6:9], v[138:141], v[204:207], v[6:9]
	v_mfma_f32_16x16x32_bf16 v[62:65], v[134:137], v[174:177], v[62:65]
	v_mfma_f32_16x16x32_bf16 v[54:57], v[142:145], v[174:177], v[54:57]
	v_mfma_f32_16x16x32_bf16 v[46:49], v[134:137], v[192:195], v[46:49]
	v_mfma_f32_16x16x32_bf16 v[38:41], v[142:145], v[192:195], v[38:41]
	v_mfma_f32_16x16x32_bf16 v[30:33], v[134:137], v[200:203], v[30:33]
	v_mfma_f32_16x16x32_bf16 v[22:25], v[142:145], v[200:203], v[22:25]
	v_mfma_f32_16x16x32_bf16 v[14:17], v[134:137], v[208:211], v[14:17]
	v_mfma_f32_16x16x32_bf16 v[6:9], v[142:145], v[208:211], v[6:9]
	s_setprio 0
	s_setprio 1
	v_mfma_f32_16x16x32_bf16 v[58:61], v[146:149], v[162:165], v[58:61]
	v_mfma_f32_16x16x32_bf16 v[50:53], v[154:157], v[162:165], v[50:53]
	v_mfma_f32_16x16x32_bf16 v[42:45], v[146:149], v[188:191], v[42:45]
	v_mfma_f32_16x16x32_bf16 v[34:37], v[154:157], v[188:191], v[34:37]
	v_mfma_f32_16x16x32_bf16 v[26:29], v[146:149], v[196:199], v[26:29]
	v_mfma_f32_16x16x32_bf16 v[18:21], v[154:157], v[196:199], v[18:21]
	v_mfma_f32_16x16x32_bf16 v[10:13], v[146:149], v[204:207], v[10:13]
	v_mfma_f32_16x16x32_bf16 v[2:5], v[154:157], v[204:207], v[2:5]
	v_mfma_f32_16x16x32_bf16 v[58:61], v[150:153], v[174:177], v[58:61]
	v_mfma_f32_16x16x32_bf16 v[50:53], v[158:161], v[174:177], v[50:53]
	v_mfma_f32_16x16x32_bf16 v[42:45], v[150:153], v[192:195], v[42:45]
	v_mfma_f32_16x16x32_bf16 v[34:37], v[158:161], v[192:195], v[34:37]
	v_mfma_f32_16x16x32_bf16 v[26:29], v[150:153], v[200:203], v[26:29]
	v_mfma_f32_16x16x32_bf16 v[18:21], v[158:161], v[200:203], v[18:21]
	v_mfma_f32_16x16x32_bf16 v[10:13], v[150:153], v[208:211], v[10:13]
	v_mfma_f32_16x16x32_bf16 v[2:5], v[158:161], v[208:211], v[2:5]
	s_setprio 0
	s_barrier
	s_add_i32 s41, s41, 2
	s_add_u32 s24, s24, 0x100
	s_addc_u32 s25, s25, 0
	s_add_u32 s40, s40, 0x100
	s_addc_u32 s52, s52, 0
	s_cmp_gt_u32 s41, 29
	s_cbranch_scc0 .LBB0_1324
	s_cmp_ge_u32 s74, 32
	s_cbranch_scc1 .Lwpf_b
	s_lshl_b32 s100, s74, 9
	v_add_u32_e32 v130, s100, v246
	v_lshrrev_b32_e32 v131, 3, v130
	v_and_b32_e32 v130, 7, v130
	v_lshlrev_b32_e32 v130, 7, v130
	v_lshl_add_u32 v130, v131, 12, v130
	s_add_u32 s100, s88, 0x1800000
	s_addc_u32 s101, s89, 0
	s_mov_b32 m0, 0x21000
	s_nop 0
	global_load_lds_dword v130, s[100:101]

;     __device__ void init(int M, int N, int G_, int c_) { nM = M / BM; nN = N / BM; nwg = nM * nN; G = launder_s(G_); c = launder_s(c_); }
; #define GRID_BAR() do { XcdBarrier b_; b_.bar = (unsigned*)(args.ws + WS_CTL); b_.x = xb_xcc_id(); b_.st = (volatile LAS unsigned*)(lds + LDS_BYTES - 64); xcd_barrier(b_); } while (0)
; #define GRID_BAR() grid.sync()
; __global__ void __launch_bounds__(NTHR, 2) mk_fwd(Args args) {
;     ...
;             GRID_BAR();
;             attn_phase(lds, QKV, positions, INF(ib + 2), INF(ib + 3), INF(ib + 4), AO, G, bid);
;             GRID_BAR();
;             { pg8::Gemm g{AO, Wo, T, D, D, D, D, 0, 0}; pg8::StaticOrder S; S.init(T, D, G, bid); pg8::EpiResidual E{hin, out, HB0, SSQ0, PTAB, nullptr}; pg8::gemm_phase(lds, g, S, E); }
.LBB0_1858:
	s_or_b64 exec, exec, s[4:5]
	v_readlane_b32 s0, v254, 52
	v_mov_b32_e32 v1, v246
	v_readlane_b32 s1, v254, 53
	s_waitcnt lgkmcnt(0)
	s_barrier
	s_cmp_ge_u32 s74, 32
	s_cbranch_scc1 .Lwpf_g
	s_lshl_b32 s100, s74, 9
	v_add_u32_e32 v212, s100, v246
	v_lshrrev_b32_e32 v213, 3, v212
	v_and_b32_e32 v212, 7, v212
	v_lshlrev_b32_e32 v212, 7, v212
	v_lshl_add_u32 v212, v213, 12, v212
	v_readlane_b32 s100, v255, 42
	s_nop 3
	s_mov_b32 s101, 0x17300000
	s_cmp_eq_u32 s100, 0
	s_cselect_b32 s101, 0x12f00000, s101
	s_add_u32 s100, s38, s101
	s_addc_u32 s101, s39, 0
	s_mov_b32 m0, 0x21000
	s_nop 0
	global_load_lds_dword v212, s[100:101]

; #define PG8_STAGE(bufoff, gbase, voff) do { _Pragma("unroll") for (int _i = 0; _i < 2; ++_i) \
;         __builtin_amdgcn_global_load_lds((const unsigned*)((const char*)(gbase) + (voff)[_i]), (LAS unsigned*)(lds + (bufoff) + ldsw + _i * 8192), 16, 0, 0); } while (0)
; #define PG8_LDA(dst, b, h) do { _Pragma("unroll") for (int m = 0; m < 4; ++m) _Pragma("unroll") for (int k = 0; k < 2; ++k) dst[m][k] = *(const LAS bf16x8*)(lds + PG8_SA(b, h) + aoff + m * 2048 + k * 1024); } while (0)
; #define PG8_LDB(dst, b, h) do { _Pragma("unroll") for (int n = 0; n < 2; ++n) _Pragma("unroll") for (int k = 0; k < 2; ++k) dst[n][k] = *(const LAS bf16x8*)(lds + PG8_SB(b, h) + boff + n * 2048 + k * 1024); } while (0)
; #define PG8_MMA(ai, bj, At, Bt) do { __builtin_amdgcn_s_setprio(1); _Pragma("unroll") for (int m = 0; m < 4; ++m) _Pragma("unroll") for (int n = 0; n < 2; ++n) _Pragma("unroll") for (int k = 0; k < 2; ++k) \
;         acc[ai][bj][m][n] = __builtin_amdgcn_mfma_f32_16x16x32_bf16(Bt[n][k], At[m][k], acc[ai][bj][m][n], 0, 0, 0); __builtin_amdgcn_s_setprio(0); } while (0)
; #define PG8_WAIT_V(n) asm volatile("s_waitcnt vmcnt(" #n ")" ::: "memory")
; #define PG8_WAIT_L(n) asm volatile("s_waitcnt lgkmcnt(" #n ")" ::: "memory")
; #define PG8_BAR __builtin_amdgcn_s_barrier()
; #define PG8_SCHED __builtin_amdgcn_sched_barrier(0)
; template <class Epi>
; __device__ __forceinline__ void gemm_phase(LAS unsigned char* lds, const Gemm g, const StaticOrder& S, const Epi& E) {
;     ...
;             PG8_LDB(B0, 0, 0); PG8_LDB(B1, 0, 1); PG8_SCHED; PG8_LDA(At, 0, 0); PG8_STAGE(PG8_SA(1, 1), a1 + hstepA, voffA);
;             PG8_WAIT_V(8); PG8_WAIT_L(0); PG8_BAR; PG8_MMA(0, 0, At, B0); PG8_MMA(0, 1, At, B1); PG8_BAR; PG8_SCHED;
;             PG8_LDA(At, 0, 1); PG8_STAGE(PG8_SB(0, 0), b2, voffB); PG8_STAGE(PG8_SB(0, 1), b2 + hstepB, voffB); PG8_STAGE(PG8_SA(0, 0), a2, voffA);
;             PG8_WAIT_V(8); PG8_WAIT_L(0); PG8_BAR; PG8_MMA(1, 0, At, B0); PG8_MMA(1, 1, At, B1); PG8_BAR; PG8_SCHED;
;             PG8_LDB(B0, 1, 0); PG8_LDB(B1, 1, 1); PG8_SCHED; PG8_LDA(At, 1, 0); PG8_STAGE(PG8_SA(0, 1), a2 + hstepA, voffA);
;             PG8_WAIT_V(8); PG8_WAIT_L(0); PG8_BAR; PG8_MMA(0, 0, At, B0); PG8_MMA(0, 1, At, B1); PG8_BAR; PG8_SCHED;
.LBB0_2035:
	s_add_u32 s14, s24, 0xfff80080
	s_addc_u32 s15, s25, -1
	s_add_i32 s41, 0, 0x10000
	s_cmp_eq_u32 s52, 28
	s_cselect_b32 s27, s1, s15
	s_cselect_b32 s26, s3, s14
	s_cselect_b32 s15, s7, s40
	s_cselect_b32 s14, s13, s17
	s_add_i32 s53, 0, 0x14000
	v_add_u32_e32 v142, s41, v1
	v_add_u32_e32 v158, s53, v1
	ds_read_b128 v[130:133], v142
	ds_read_b128 v[134:137], v142 offset:1024
	ds_read_b128 v[138:141], v142 offset:2048
	ds_read_b128 v[142:145], v142 offset:3072
	ds_read_b128 v[146:149], v158
	ds_read_b128 v[150:153], v158 offset:1024
	ds_read_b128 v[154:157], v158 offset:2048
	ds_read_b128 v[158:161], v158 offset:3072
	v_lshl_add_u64 v[178:179], s[24:25], 0, v[196:197]
	s_add_i32 m0, s23, 0xc000
	ds_read_b128 v[162:165], v181
	ds_read_b128 v[166:169], v181 offset:1024
	ds_read_b128 v[170:173], v181 offset:2048
	ds_read_b128 v[174:177], v181 offset:3072
	ds_read_b128 v[200:203], v181 offset:4096
	ds_read_b128 v[204:207], v181 offset:5120
	ds_read_b128 v[208:211], v181 offset:6144
	ds_read_b128 v[212:215], v181 offset:7168
	global_load_lds_dwordx4 v[178:179], off
	v_lshl_add_u64 v[178:179], s[24:25], 0, v[198:199]
	s_add_i32 m0, s23, 0xe000
	s_nop 0
	global_load_lds_dwordx4 v[178:179], off
	s_waitcnt vmcnt(8)
	s_waitcnt lgkmcnt(0)
	s_barrier
	s_setprio 1
	s_waitcnt lgkmcnt(0)
	v_mfma_f32_16x16x32_bf16 v[126:129], v[130:133], v[162:165], v[126:129]
	v_mfma_f32_16x16x32_bf16 v[122:125], v[138:141], v[162:165], v[122:125]
	v_mfma_f32_16x16x32_bf16 v[110:113], v[130:133], v[170:173], v[110:113]
	v_mfma_f32_16x16x32_bf16 v[106:109], v[138:141], v[170:173], v[106:109]
	v_mfma_f32_16x16x32_bf16 v[94:97], v[130:133], v[200:203], v[94:97]
	v_mfma_f32_16x16x32_bf16 v[90:93], v[138:141], v[200:203], v[90:93]
	v_mfma_f32_16x16x32_bf16 v[82:85], v[130:133], v[208:211], v[82:85]
	v_mfma_f32_16x16x32_bf16 v[74:77], v[138:141], v[208:211], v[74:77]
	v_mfma_f32_16x16x32_bf16 v[126:129], v[134:137], v[166:169], v[126:129]
	v_mfma_f32_16x16x32_bf16 v[122:125], v[142:145], v[166:169], v[122:125]
	v_mfma_f32_16x16x32_bf16 v[110:113], v[134:137], v[174:177], v[110:113]
	v_mfma_f32_16x16x32_bf16 v[106:109], v[142:145], v[174:177], v[106:109]
	v_mfma_f32_16x16x32_bf16 v[94:97], v[134:137], v[204:207], v[94:97]
	v_mfma_f32_16x16x32_bf16 v[90:93], v[142:145], v[204:207], v[90:93]
	v_mfma_f32_16x16x32_bf16 v[82:85], v[134:137], v[212:215], v[82:85]
	v_mfma_f32_16x16x32_bf16 v[74:77], v[142:145], v[212:215], v[74:77]
	s_setprio 0
	s_setprio 1
	v_mfma_f32_16x16x32_bf16 v[118:121], v[146:149], v[162:165], v[118:121]
	v_mfma_f32_16x16x32_bf16 v[114:117], v[154:157], v[162:165], v[114:117]
	v_mfma_f32_16x16x32_bf16 v[102:105], v[146:149], v[170:173], v[102:105]
	v_mfma_f32_16x16x32_bf16 v[98:101], v[154:157], v[170:173], v[98:101]
	v_mfma_f32_16x16x32_bf16 v[86:89], v[146:149], v[200:203], v[86:89]
	v_mfma_f32_16x16x32_bf16 v[78:81], v[154:157], v[200:203], v[78:81]
	v_mfma_f32_16x16x32_bf16 v[70:73], v[146:149], v[208:211], v[70:73]
	v_mfma_f32_16x16x32_bf16 v[66:69], v[154:157], v[208:211], v[66:69]
	v_mfma_f32_16x16x32_bf16 v[118:121], v[150:153], v[166:169], v[118:121]
	v_mfma_f32_16x16x32_bf16 v[114:117], v[158:161], v[166:169], v[114:117]
	v_mfma_f32_16x16x32_bf16 v[102:105], v[150:153], v[174:177], v[102:105]
	v_mfma_f32_16x16x32_bf16 v[98:101], v[158:161], v[174:177], v[98:101]
	v_mfma_f32_16x16x32_bf16 v[86:89], v[150:153], v[204:207], v[86:89]
	v_mfma_f32_16x16x32_bf16 v[78:81], v[158:161], v[204:207], v[78:81]
	v_mfma_f32_16x16x32_bf16 v[70:73], v[150:153], v[212:215], v[70:73]
	v_mfma_f32_16x16x32_bf16 v[66:69], v[158:161], v[212:215], v[66:69]
	s_setprio 0
	s_barrier
	s_add_i32 s41, s41, s30
	v_lshl_add_u64 v[178:179], s[14:15], 0, v[190:191]
	s_mov_b32 m0, s41
	ds_read_b128 v[162:165], v181 offset:16384
	ds_read_b128 v[166:169], v181 offset:17408
	ds_read_b128 v[170:173], v181 offset:18432
	ds_read_b128 v[174:177], v181 offset:19456
	ds_read_b128 v[200:203], v181 offset:20480
	ds_read_b128 v[204:207], v181 offset:21504
	ds_read_b128 v[208:211], v181 offset:22528
	ds_read_b128 v[212:215], v181 offset:23552
	global_load_lds_dwordx4 v[178:179], off
	s_add_i32 m0, s41, 0x2000
	s_add_u32 s62, s14, 0x80000
	v_lshl_add_u64 v[184:185], s[14:15], 0, v[194:195]
	s_addc_u32 s63, s15, 0
	s_add_i32 s41, s53, s30
	global_load_lds_dwordx4 v[184:185], off
	v_lshl_add_u64 v[216:217], s[62:63], 0, v[190:191]
	s_mov_b32 m0, s41
	v_lshl_add_u64 v[218:219], s[26:27], 0, v[192:193]
	global_load_lds_dwordx4 v[216:217], off
	v_lshl_add_u64 v[216:217], s[62:63], 0, v[194:195]
	s_add_i32 m0, s41, 0x2000
	s_nop 0
	global_load_lds_dwordx4 v[216:217], off
	v_lshl_add_u64 v[216:217], s[26:27], 0, v[188:189]
	s_mov_b32 m0, s23
	s_nop 0
	global_load_lds_dwordx4 v[216:217], off
	s_mov_b32 m0, s34
	s_nop 0
	global_load_lds_dwordx4 v[218:219], off
	s_waitcnt vmcnt(8)
	s_waitcnt lgkmcnt(0)
	s_barrier
; #define PG8_STAGE(bufoff, gbase, voff) do { _Pragma("unroll") for (int _i = 0; _i < 2; ++_i) \
;         __builtin_amdgcn_global_load_lds((const unsigned*)((const char*)(gbase) + (voff)[_i]), (LAS unsigned*)(lds + (bufoff) + ldsw + _i * 8192), 16, 0, 0); } while (0)
; #define PG8_LDA(dst, b, h) do { _Pragma("unroll") for (int m = 0; m < 4; ++m) _Pragma("unroll") for (int k = 0; k < 2; ++k) dst[m][k] = *(const LAS bf16x8*)(lds + PG8_SA(b, h) + aoff + m * 2048 + k * 1024); } while (0)
; #define PG8_LDB(dst, b, h) do { _Pragma("unroll") for (int n = 0; n < 2; ++n) _Pragma("unroll") for (int k = 0; k < 2; ++k) dst[n][k] = *(const LAS bf16x8*)(lds + PG8_SB(b, h) + boff + n * 2048 + k * 1024); } while (0)
; #define PG8_MMA(ai, bj, At, Bt) do { __builtin_amdgcn_s_setprio(1); _Pragma("unroll") for (int m = 0; m < 4; ++m) _Pragma("unroll") for (int n = 0; n < 2; ++n) _Pragma("unroll") for (int k = 0; k < 2; ++k) \
;         acc[ai][bj][m][n] = __builtin_amdgcn_mfma_f32_16x16x32_bf16(Bt[n][k], At[m][k], acc[ai][bj][m][n], 0, 0, 0); __builtin_amdgcn_s_setprio(0); } while (0)
; #define PG8_WAIT_V(n) asm volatile("s_waitcnt vmcnt(" #n ")" ::: "memory")
; #define PG8_WAIT_L(n) asm volatile("s_waitcnt lgkmcnt(" #n ")" ::: "memory")
; #define PG8_BAR __builtin_amdgcn_s_barrier()
; #define PG8_SCHED __builtin_amdgcn_sched_barrier(0)
; template <class Epi>
; __device__ __forceinline__ void gemm_phase(LAS unsigned char* lds, const Gemm g, const StaticOrder& S, const Epi& E) {
;     ...
;             PG8_WAIT_V(8); PG8_WAIT_L(0); PG8_BAR; PG8_MMA(1, 0, At, B0); PG8_MMA(1, 1, At, B1); PG8_BAR; PG8_SCHED;
;             PG8_LDB(B0, 1, 0); PG8_LDB(B1, 1, 1); PG8_SCHED; PG8_LDA(At, 1, 0); PG8_STAGE(PG8_SA(0, 1), a2 + hstepA, voffA);
;             PG8_WAIT_V(8); PG8_WAIT_L(0); PG8_BAR; PG8_MMA(0, 0, At, B0); PG8_MMA(0, 1, At, B1); PG8_BAR; PG8_SCHED;
;             PG8_LDA(At, 1, 1); PG8_STAGE(PG8_SB(1, 0), b3, voffB); PG8_STAGE(PG8_SB(1, 1), b3 + hstepB, voffB); PG8_STAGE(PG8_SA(1, 0), a3, voffA);
	s_setprio 1
	s_waitcnt lgkmcnt(0)
	v_mfma_f32_16x16x32_bf16 v[62:65], v[130:133], v[162:165], v[62:65]
	v_mfma_f32_16x16x32_bf16 v[58:61], v[138:141], v[162:165], v[58:61]
	v_mfma_f32_16x16x32_bf16 v[50:53], v[130:133], v[170:173], v[50:53]
	v_mfma_f32_16x16x32_bf16 v[42:45], v[138:141], v[170:173], v[42:45]
	v_mfma_f32_16x16x32_bf16 v[30:33], v[130:133], v[200:203], v[30:33]
	v_mfma_f32_16x16x32_bf16 v[26:29], v[138:141], v[200:203], v[26:29]
	v_mfma_f32_16x16x32_bf16 v[18:21], v[130:133], v[208:211], v[18:21]
	v_mfma_f32_16x16x32_bf16 v[10:13], v[138:141], v[208:211], v[10:13]
	v_mfma_f32_16x16x32_bf16 v[62:65], v[134:137], v[166:169], v[62:65]
	v_mfma_f32_16x16x32_bf16 v[58:61], v[142:145], v[166:169], v[58:61]
	v_mfma_f32_16x16x32_bf16 v[50:53], v[134:137], v[174:177], v[50:53]
	v_mfma_f32_16x16x32_bf16 v[42:45], v[142:145], v[174:177], v[42:45]
	v_mfma_f32_16x16x32_bf16 v[30:33], v[134:137], v[204:207], v[30:33]
	v_mfma_f32_16x16x32_bf16 v[26:29], v[142:145], v[204:207], v[26:29]
	v_mfma_f32_16x16x32_bf16 v[18:21], v[134:137], v[212:215], v[18:21]
	v_mfma_f32_16x16x32_bf16 v[10:13], v[142:145], v[212:215], v[10:13]
	s_setprio 0
	s_setprio 1
	v_mfma_f32_16x16x32_bf16 v[54:57], v[146:149], v[162:165], v[54:57]
	v_mfma_f32_16x16x32_bf16 v[46:49], v[154:157], v[162:165], v[46:49]
	v_mfma_f32_16x16x32_bf16 v[38:41], v[146:149], v[170:173], v[38:41]
	v_mfma_f32_16x16x32_bf16 v[34:37], v[154:157], v[170:173], v[34:37]
	v_mfma_f32_16x16x32_bf16 v[22:25], v[146:149], v[200:203], v[22:25]
	v_mfma_f32_16x16x32_bf16 v[14:17], v[154:157], v[200:203], v[14:17]
	v_mfma_f32_16x16x32_bf16 v[6:9], v[146:149], v[208:211], v[6:9]
	v_mfma_f32_16x16x32_bf16 v[2:5], v[154:157], v[208:211], v[2:5]
	v_mfma_f32_16x16x32_bf16 v[54:57], v[150:153], v[166:169], v[54:57]
	v_mfma_f32_16x16x32_bf16 v[46:49], v[158:161], v[166:169], v[46:49]
	v_mfma_f32_16x16x32_bf16 v[38:41], v[150:153], v[174:177], v[38:41]
	v_mfma_f32_16x16x32_bf16 v[34:37], v[158:161], v[174:177], v[34:37]
	v_mfma_f32_16x16x32_bf16 v[22:25], v[150:153], v[204:207], v[22:25]
	v_mfma_f32_16x16x32_bf16 v[14:17], v[158:161], v[204:207], v[14:17]
	v_mfma_f32_16x16x32_bf16 v[6:9], v[150:153], v[212:215], v[6:9]
	v_mfma_f32_16x16x32_bf16 v[2:5], v[158:161], v[212:215], v[2:5]
	s_setprio 0
	s_barrier
	s_add_i32 s41, 0, 0x18000
	s_add_i32 s53, 0, 0x1c000
	v_add_u32_e32 v142, s41, v1
	v_add_u32_e32 v158, s53, v1
	ds_read_b128 v[130:133], v142
	ds_read_b128 v[134:137], v142 offset:1024
	ds_read_b128 v[138:141], v142 offset:2048
	ds_read_b128 v[142:145], v142 offset:3072
	ds_read_b128 v[146:149], v158
	ds_read_b128 v[150:153], v158 offset:1024
	ds_read_b128 v[154:157], v158 offset:2048
	ds_read_b128 v[158:161], v158 offset:3072
	s_add_u32 s26, s26, 0x80000
	s_addc_u32 s27, s27, 0
	s_mov_b32 m0, s35
	v_lshl_add_u64 v[220:221], s[26:27], 0, v[188:189]
	ds_read_b128 v[162:165], v181 offset:32768
	ds_read_b128 v[166:169], v181 offset:33792
	ds_read_b128 v[170:173], v181 offset:34816
	ds_read_b128 v[174:177], v181 offset:35840
	ds_read_b128 v[200:203], v181 offset:36864
	ds_read_b128 v[204:207], v181 offset:37888
	ds_read_b128 v[208:211], v181 offset:38912
	ds_read_b128 v[212:215], v181 offset:39936
	global_load_lds_dwordx4 v[220:221], off
	v_lshl_add_u64 v[220:221], s[26:27], 0, v[192:193]
	s_mov_b32 m0, s42
	s_nop 0
	global_load_lds_dwordx4 v[220:221], off
	s_waitcnt vmcnt(8)
	s_waitcnt lgkmcnt(0)
	s_barrier
	s_setprio 1
	s_waitcnt lgkmcnt(0)
	v_mfma_f32_16x16x32_bf16 v[126:129], v[130:133], v[162:165], v[126:129]
	v_mfma_f32_16x16x32_bf16 v[122:125], v[138:141], v[162:165], v[122:125]
	v_mfma_f32_16x16x32_bf16 v[110:113], v[130:133], v[170:173], v[110:113]
	v_mfma_f32_16x16x32_bf16 v[106:109], v[138:141], v[170:173], v[106:109]
	v_mfma_f32_16x16x32_bf16 v[94:97], v[130:133], v[200:203], v[94:97]
	v_mfma_f32_16x16x32_bf16 v[90:93], v[138:141], v[200:203], v[90:93]
	v_mfma_f32_16x16x32_bf16 v[82:85], v[130:133], v[208:211], v[82:85]
	v_mfma_f32_16x16x32_bf16 v[74:77], v[138:141], v[208:211], v[74:77]
	v_mfma_f32_16x16x32_bf16 v[126:129], v[134:137], v[166:169], v[126:129]
	v_mfma_f32_16x16x32_bf16 v[122:125], v[142:145], v[166:169], v[122:125]
	v_mfma_f32_16x16x32_bf16 v[110:113], v[134:137], v[174:177], v[110:113]
	v_mfma_f32_16x16x32_bf16 v[106:109], v[142:145], v[174:177], v[106:109]
	v_mfma_f32_16x16x32_bf16 v[94:97], v[134:137], v[204:207], v[94:97]
	v_mfma_f32_16x16x32_bf16 v[90:93], v[142:145], v[204:207], v[90:93]
	v_mfma_f32_16x16x32_bf16 v[82:85], v[134:137], v[212:215], v[82:85]
	v_mfma_f32_16x16x32_bf16 v[74:77], v[142:145], v[212:215], v[74:77]
	s_setprio 0
	s_setprio 1
	v_mfma_f32_16x16x32_bf16 v[118:121], v[146:149], v[162:165], v[118:121]
	v_mfma_f32_16x16x32_bf16 v[114:117], v[154:157], v[162:165], v[114:117]
	v_mfma_f32_16x16x32_bf16 v[102:105], v[146:149], v[170:173], v[102:105]
	v_mfma_f32_16x16x32_bf16 v[98:101], v[154:157], v[170:173], v[98:101]
	v_mfma_f32_16x16x32_bf16 v[86:89], v[146:149], v[200:203], v[86:89]
	v_mfma_f32_16x16x32_bf16 v[78:81], v[154:157], v[200:203], v[78:81]
	v_mfma_f32_16x16x32_bf16 v[70:73], v[146:149], v[208:211], v[70:73]
	v_mfma_f32_16x16x32_bf16 v[66:69], v[154:157], v[208:211], v[66:69]
	v_mfma_f32_16x16x32_bf16 v[118:121], v[150:153], v[166:169], v[118:121]
	v_mfma_f32_16x16x32_bf16 v[114:117], v[158:161], v[166:169], v[114:117]
	v_mfma_f32_16x16x32_bf16 v[102:105], v[150:153], v[174:177], v[102:105]
	v_mfma_f32_16x16x32_bf16 v[98:101], v[158:161], v[174:177], v[98:101]
	v_mfma_f32_16x16x32_bf16 v[86:89], v[150:153], v[204:207], v[86:89]
	v_mfma_f32_16x16x32_bf16 v[78:81], v[158:161], v[204:207], v[78:81]
	v_mfma_f32_16x16x32_bf16 v[70:73], v[150:153], v[212:215], v[70:73]
	v_mfma_f32_16x16x32_bf16 v[66:69], v[158:161], v[212:215], v[66:69]
	s_setprio 0
	s_barrier
; #define PG8_STAGE(bufoff, gbase, voff) do { _Pragma("unroll") for (int _i = 0; _i < 2; ++_i) \
;         __builtin_amdgcn_global_load_lds((const unsigned*)((const char*)(gbase) + (voff)[_i]), (LAS unsigned*)(lds + (bufoff) + ldsw + _i * 8192), 16, 0, 0); } while (0)
; #define PG8_LDA(dst, b, h) do { _Pragma("unroll") for (int m = 0; m < 4; ++m) _Pragma("unroll") for (int k = 0; k < 2; ++k) dst[m][k] = *(const LAS bf16x8*)(lds + PG8_SA(b, h) + aoff + m * 2048 + k * 1024); } while (0)
; #define PG8_LDB(dst, b, h) do { _Pragma("unroll") for (int n = 0; n < 2; ++n) _Pragma("unroll") for (int k = 0; k < 2; ++k) dst[n][k] = *(const LAS bf16x8*)(lds + PG8_SB(b, h) + boff + n * 2048 + k * 1024); } while (0)
; #define PG8_MMA(ai, bj, At, Bt) do { __builtin_amdgcn_s_setprio(1); _Pragma("unroll") for (int m = 0; m < 4; ++m) _Pragma("unroll") for (int n = 0; n < 2; ++n) _Pragma("unroll") for (int k = 0; k < 2; ++k) \
;         acc[ai][bj][m][n] = __builtin_amdgcn_mfma_f32_16x16x32_bf16(Bt[n][k], At[m][k], acc[ai][bj][m][n], 0, 0, 0); __builtin_amdgcn_s_setprio(0); } while (0)
; #define PG8_WAIT_V(n) asm volatile("s_waitcnt vmcnt(" #n ")" ::: "memory")
; #define PG8_BAR __builtin_amdgcn_s_barrier()
; template <class Epi>
; __device__ __forceinline__ void gemm_phase(LAS unsigned char* lds, const Gemm g, const StaticOrder& S, const Epi& E) {
;     ...
;             PG8_LDB(B0, 0, 0); PG8_LDB(B1, 0, 1); PG8_SCHED; PG8_LDA(At, 0, 0); PG8_STAGE(PG8_SA(1, 1), a1 + hstepA, voffA);
;             PG8_WAIT_V(8); PG8_WAIT_L(0); PG8_BAR; PG8_MMA(0, 0, At, B0); PG8_MMA(0, 1, At, B1); PG8_BAR; PG8_SCHED;
;             PG8_LDA(At, 0, 1); PG8_STAGE(PG8_SB(0, 0), b2, voffB); PG8_STAGE(PG8_SB(0, 1), b2 + hstepB, voffB); PG8_STAGE(PG8_SA(0, 0), a2, voffA);
;             PG8_WAIT_V(8); PG8_WAIT_L(0); PG8_BAR; PG8_MMA(1, 0, At, B0); PG8_MMA(1, 1, At, B1); PG8_BAR; PG8_SCHED;
;             PG8_LDB(B0, 1, 0); PG8_LDB(B1, 1, 1); PG8_SCHED; PG8_LDA(At, 1, 0); PG8_STAGE(PG8_SA(0, 1), a2 + hstepA, voffA);
;             PG8_WAIT_V(8); PG8_WAIT_L(0); PG8_BAR; PG8_MMA(0, 0, At, B0); PG8_MMA(0, 1, At, B1); PG8_BAR; PG8_SCHED;
;             PG8_LDA(At, 1, 1); PG8_STAGE(PG8_SB(1, 0), b3, voffB); PG8_STAGE(PG8_SB(1, 1), b3 + hstepB, voffB); PG8_STAGE(PG8_SA(1, 0), a3, voffA);
;             PG8_WAIT_V(8); PG8_WAIT_L(0); PG8_BAR; PG8_MMA(1, 0, At, B0); PG8_MMA(1, 1, At, B1); PG8_BAR; PG8_SCHED;
;         }
	s_add_i32 s26, s41, s30
	v_lshl_add_u64 v[178:179], v[178:179], 0, s[84:85]
	s_mov_b32 m0, s26
	ds_read_b128 v[162:165], v181 offset:49152
	ds_read_b128 v[166:169], v181 offset:50176
	ds_read_b128 v[170:173], v181 offset:51200
	ds_read_b128 v[174:177], v181 offset:52224
	ds_read_b128 v[200:203], v181 offset:53248
	ds_read_b128 v[204:207], v181 offset:54272
	ds_read_b128 v[208:211], v181 offset:55296
	ds_read_b128 v[212:215], v181 offset:56320
	global_load_lds_dwordx4 v[178:179], off
	s_add_i32 m0, s26, 0x2000
	s_add_u32 s14, s14, 0x80080
	v_lshl_add_u64 v[178:179], v[184:185], 0, s[84:85]
	s_addc_u32 s15, s15, 0
	s_add_i32 s26, s53, s30
	global_load_lds_dwordx4 v[178:179], off
	v_lshl_add_u64 v[178:179], s[14:15], 0, v[190:191]
	s_mov_b32 m0, s26
	s_nop 0
	global_load_lds_dwordx4 v[178:179], off
	v_lshl_add_u64 v[178:179], s[14:15], 0, v[194:195]
	s_add_i32 m0, s26, 0x2000
	s_nop 0
	global_load_lds_dwordx4 v[178:179], off
	v_lshl_add_u64 v[178:179], v[216:217], 0, s[84:85]
	s_mov_b32 m0, s68
	s_nop 0
	global_load_lds_dwordx4 v[178:179], off
	v_lshl_add_u64 v[178:179], v[218:219], 0, s[84:85]
	s_mov_b32 m0, s69
	s_nop 0
	global_load_lds_dwordx4 v[178:179], off
	s_waitcnt vmcnt(8)
	s_waitcnt lgkmcnt(0)
	s_barrier
	s_setprio 1
	s_waitcnt lgkmcnt(0)
	v_mfma_f32_16x16x32_bf16 v[62:65], v[130:133], v[162:165], v[62:65]
	v_mfma_f32_16x16x32_bf16 v[58:61], v[138:141], v[162:165], v[58:61]
	v_mfma_f32_16x16x32_bf16 v[50:53], v[130:133], v[170:173], v[50:53]
	v_mfma_f32_16x16x32_bf16 v[42:45], v[138:141], v[170:173], v[42:45]
	v_mfma_f32_16x16x32_bf16 v[30:33], v[130:133], v[200:203], v[30:33]
	v_mfma_f32_16x16x32_bf16 v[26:29], v[138:141], v[200:203], v[26:29]
	v_mfma_f32_16x16x32_bf16 v[18:21], v[130:133], v[208:211], v[18:21]
	v_mfma_f32_16x16x32_bf16 v[10:13], v[138:141], v[208:211], v[10:13]
	v_mfma_f32_16x16x32_bf16 v[62:65], v[134:137], v[166:169], v[62:65]
	v_mfma_f32_16x16x32_bf16 v[58:61], v[142:145], v[166:169], v[58:61]
	v_mfma_f32_16x16x32_bf16 v[50:53], v[134:137], v[174:177], v[50:53]
	v_mfma_f32_16x16x32_bf16 v[42:45], v[142:145], v[174:177], v[42:45]
	v_mfma_f32_16x16x32_bf16 v[30:33], v[134:137], v[204:207], v[30:33]
	v_mfma_f32_16x16x32_bf16 v[26:29], v[142:145], v[204:207], v[26:29]
	v_mfma_f32_16x16x32_bf16 v[18:21], v[134:137], v[212:215], v[18:21]
	v_mfma_f32_16x16x32_bf16 v[10:13], v[142:145], v[212:215], v[10:13]
	s_setprio 0
	s_setprio 1
	v_mfma_f32_16x16x32_bf16 v[54:57], v[146:149], v[162:165], v[54:57]
	v_mfma_f32_16x16x32_bf16 v[46:49], v[154:157], v[162:165], v[46:49]
	v_mfma_f32_16x16x32_bf16 v[38:41], v[146:149], v[170:173], v[38:41]
	v_mfma_f32_16x16x32_bf16 v[34:37], v[154:157], v[170:173], v[34:37]
	v_mfma_f32_16x16x32_bf16 v[22:25], v[146:149], v[200:203], v[22:25]
	v_mfma_f32_16x16x32_bf16 v[14:17], v[154:157], v[200:203], v[14:17]
	v_mfma_f32_16x16x32_bf16 v[6:9], v[146:149], v[208:211], v[6:9]
	v_mfma_f32_16x16x32_bf16 v[2:5], v[154:157], v[208:211], v[2:5]
	v_mfma_f32_16x16x32_bf16 v[54:57], v[150:153], v[166:169], v[54:57]
	v_mfma_f32_16x16x32_bf16 v[46:49], v[158:161], v[166:169], v[46:49]
	v_mfma_f32_16x16x32_bf16 v[38:41], v[150:153], v[174:177], v[38:41]
	v_mfma_f32_16x16x32_bf16 v[34:37], v[158:161], v[174:177], v[34:37]
	v_mfma_f32_16x16x32_bf16 v[22:25], v[150:153], v[204:207], v[22:25]
	v_mfma_f32_16x16x32_bf16 v[14:17], v[158:161], v[204:207], v[14:17]
	v_mfma_f32_16x16x32_bf16 v[6:9], v[150:153], v[212:215], v[6:9]
	v_mfma_f32_16x16x32_bf16 v[2:5], v[158:161], v[212:215], v[2:5]
	s_setprio 0
	s_barrier
	s_add_i32 s52, s52, 2
	s_add_u32 s24, s24, 0x100
	s_addc_u32 s25, s25, 0
	s_add_u32 s17, s17, 0x100
	s_addc_u32 s40, s40, 0
	s_cmp_gt_u32 s52, 29
	s_cbranch_scc0 .LBB0_2035
	s_cmp_ge_u32 s74, 32
	s_cbranch_scc1 .Lwpf_c
	s_lshl_b32 s100, s74, 9
	v_add_u32_e32 v130, s100, v246
	v_lshrrev_b32_e32 v131, 3, v130
	v_and_b32_e32 v130, 7, v130
	v_lshlrev_b32_e32 v130, 7, v130
	v_lshl_add_u32 v130, v131, 12, v130
	s_add_u32 s100, s88, 0x1800000
	s_addc_u32 s101, s89, 0
	s_mov_b32 m0, 0x21000
	s_nop 0
	global_load_lds_dword v130, s[100:101]

; #define PG8_STAGE(bufoff, gbase, voff) do { _Pragma("unroll") for (int _i = 0; _i < 2; ++_i) \
;         __builtin_amdgcn_global_load_lds((const unsigned*)((const char*)(gbase) + (voff)[_i]), (LAS unsigned*)(lds + (bufoff) + ldsw + _i * 8192), 16, 0, 0); } while (0)
; #define PG8_LDA(dst, b, h) do { _Pragma("unroll") for (int m = 0; m < 4; ++m) _Pragma("unroll") for (int k = 0; k < 2; ++k) dst[m][k] = *(const LAS bf16x8*)(lds + PG8_SA(b, h) + aoff + m * 2048 + k * 1024); } while (0)
; #define PG8_LDB(dst, b, h) do { _Pragma("unroll") for (int n = 0; n < 2; ++n) _Pragma("unroll") for (int k = 0; k < 2; ++k) dst[n][k] = *(const LAS bf16x8*)(lds + PG8_SB(b, h) + boff + n * 2048 + k * 1024); } while (0)
; #define PG8_MMA(ai, bj, At, Bt) do { __builtin_amdgcn_s_setprio(1); _Pragma("unroll") for (int m = 0; m < 4; ++m) _Pragma("unroll") for (int n = 0; n < 2; ++n) _Pragma("unroll") for (int k = 0; k < 2; ++k) \
;         acc[ai][bj][m][n] = __builtin_amdgcn_mfma_f32_16x16x32_bf16(Bt[n][k], At[m][k], acc[ai][bj][m][n], 0, 0, 0); __builtin_amdgcn_s_setprio(0); } while (0)
; #define PG8_WAIT_V(n) asm volatile("s_waitcnt vmcnt(" #n ")" ::: "memory")
; #define PG8_WAIT_L(n) asm volatile("s_waitcnt lgkmcnt(" #n ")" ::: "memory")
; #define PG8_BAR __builtin_amdgcn_s_barrier()
; #define PG8_SCHED __builtin_amdgcn_sched_barrier(0)
; template <class Epi>
; __device__ __forceinline__ void gemm_phase(LAS unsigned char* lds, const Gemm g, const StaticOrder& S, const Epi& E) {
;     ...
;             PG8_LDB(B0, 0, 0); PG8_LDB(B1, 0, 1); PG8_SCHED; PG8_LDA(At, 0, 0); PG8_STAGE(PG8_SA(1, 1), a1 + hstepA, voffA);
;             PG8_WAIT_V(8); PG8_WAIT_L(0); PG8_BAR; PG8_MMA(0, 0, At, B0); PG8_MMA(0, 1, At, B1); PG8_BAR; PG8_SCHED;
;             PG8_LDA(At, 0, 1); PG8_STAGE(PG8_SB(0, 0), b2, voffB); PG8_STAGE(PG8_SB(0, 1), b2 + hstepB, voffB); PG8_STAGE(PG8_SA(0, 0), a2, voffA);
;             PG8_WAIT_V(8); PG8_WAIT_L(0); PG8_BAR; PG8_MMA(1, 0, At, B0); PG8_MMA(1, 1, At, B1); PG8_BAR; PG8_SCHED;
;             PG8_LDB(B0, 1, 0); PG8_LDB(B1, 1, 1); PG8_SCHED; PG8_LDA(At, 1, 0); PG8_STAGE(PG8_SA(0, 1), a2 + hstepA, voffA);
;             PG8_WAIT_V(8); PG8_WAIT_L(0); PG8_BAR; PG8_MMA(0, 0, At, B0); PG8_MMA(0, 1, At, B1); PG8_BAR; PG8_SCHED;
.LBB0_2130:
	s_add_u32 s14, s20, 0xfff80080
	s_addc_u32 s15, s21, -1
	s_add_i32 s62, 0, 0x10000
	s_cmp_eq_u32 s41, 28
	s_cselect_b32 s23, s3, s15
	s_cselect_b32 s22, s11, s14
	v_add_u32_e32 v142, s62, v1
	s_cselect_b32 s15, s9, s53
	s_cselect_b32 s14, s40, s52
	s_add_i32 s64, 0, 0x14000
	ds_read_b128 v[146:149], v142
	ds_read_b128 v[150:153], v142 offset:1024
	ds_read_b128 v[154:157], v142 offset:2048
	ds_read_b128 v[158:161], v142 offset:3072
	v_add_u32_e32 v142, s64, v1
	ds_read_b128 v[162:165], v142
	ds_read_b128 v[166:169], v142 offset:1024
	ds_read_b128 v[170:173], v142 offset:2048
	ds_read_b128 v[174:177], v142 offset:3072
	v_lshl_add_u64 v[142:143], s[20:21], 0, v[138:139]
	s_add_i32 m0, s19, 0xc000
	ds_read_b128 v[188:191], v144
	ds_read_b128 v[192:195], v144 offset:1024
	ds_read_b128 v[196:199], v144 offset:2048
	ds_read_b128 v[200:203], v144 offset:3072
	ds_read_b128 v[204:207], v144 offset:4096
	ds_read_b128 v[208:211], v144 offset:5120
	ds_read_b128 v[212:215], v144 offset:6144
	ds_read_b128 v[216:219], v144 offset:7168
	global_load_lds_dwordx4 v[142:143], off
	v_lshl_add_u64 v[142:143], s[20:21], 0, v[140:141]
	s_add_i32 m0, s19, 0xe000
	s_nop 0
	global_load_lds_dwordx4 v[142:143], off
	s_waitcnt vmcnt(8)
	s_waitcnt lgkmcnt(0)
	s_barrier
	s_setprio 1
	s_waitcnt lgkmcnt(0)
	v_mfma_f32_16x16x32_bf16 v[126:129], v[146:149], v[188:191], v[126:129]
	v_mfma_f32_16x16x32_bf16 v[122:125], v[154:157], v[188:191], v[122:125]
	v_mfma_f32_16x16x32_bf16 v[110:113], v[146:149], v[196:199], v[110:113]
	v_mfma_f32_16x16x32_bf16 v[106:109], v[154:157], v[196:199], v[106:109]
	v_mfma_f32_16x16x32_bf16 v[94:97], v[146:149], v[204:207], v[94:97]
	v_mfma_f32_16x16x32_bf16 v[90:93], v[154:157], v[204:207], v[90:93]
	v_mfma_f32_16x16x32_bf16 v[78:81], v[146:149], v[212:215], v[78:81]
	v_mfma_f32_16x16x32_bf16 v[74:77], v[154:157], v[212:215], v[74:77]
	v_mfma_f32_16x16x32_bf16 v[126:129], v[150:153], v[192:195], v[126:129]
	v_mfma_f32_16x16x32_bf16 v[122:125], v[158:161], v[192:195], v[122:125]
	v_mfma_f32_16x16x32_bf16 v[110:113], v[150:153], v[200:203], v[110:113]
	v_mfma_f32_16x16x32_bf16 v[106:109], v[158:161], v[200:203], v[106:109]
	v_mfma_f32_16x16x32_bf16 v[94:97], v[150:153], v[208:211], v[94:97]
	v_mfma_f32_16x16x32_bf16 v[90:93], v[158:161], v[208:211], v[90:93]
	v_mfma_f32_16x16x32_bf16 v[78:81], v[150:153], v[216:219], v[78:81]
	v_mfma_f32_16x16x32_bf16 v[74:77], v[158:161], v[216:219], v[74:77]
	s_setprio 0
	s_setprio 1
	v_mfma_f32_16x16x32_bf16 v[118:121], v[162:165], v[188:191], v[118:121]
	v_mfma_f32_16x16x32_bf16 v[114:117], v[170:173], v[188:191], v[114:117]
	v_mfma_f32_16x16x32_bf16 v[102:105], v[162:165], v[196:199], v[102:105]
	v_mfma_f32_16x16x32_bf16 v[98:101], v[170:173], v[196:199], v[98:101]
	v_mfma_f32_16x16x32_bf16 v[86:89], v[162:165], v[204:207], v[86:89]
	v_mfma_f32_16x16x32_bf16 v[82:85], v[170:173], v[204:207], v[82:85]
	v_mfma_f32_16x16x32_bf16 v[70:73], v[162:165], v[212:215], v[70:73]
	v_mfma_f32_16x16x32_bf16 v[66:69], v[170:173], v[212:215], v[66:69]
	v_mfma_f32_16x16x32_bf16 v[118:121], v[166:169], v[192:195], v[118:121]
	v_mfma_f32_16x16x32_bf16 v[114:117], v[174:177], v[192:195], v[114:117]
	v_mfma_f32_16x16x32_bf16 v[102:105], v[166:169], v[200:203], v[102:105]
	v_mfma_f32_16x16x32_bf16 v[98:101], v[174:177], v[200:203], v[98:101]
	v_mfma_f32_16x16x32_bf16 v[86:89], v[166:169], v[208:211], v[86:89]
	v_mfma_f32_16x16x32_bf16 v[82:85], v[174:177], v[208:211], v[82:85]
	v_mfma_f32_16x16x32_bf16 v[70:73], v[166:169], v[216:219], v[70:73]
	v_mfma_f32_16x16x32_bf16 v[66:69], v[174:177], v[216:219], v[66:69]
	s_setprio 0
	s_barrier
	s_add_i32 s62, s62, s27
	v_lshl_add_u64 v[142:143], s[14:15], 0, v[132:133]
	s_mov_b32 m0, s62
	ds_read_b128 v[188:191], v144 offset:16384
	ds_read_b128 v[192:195], v144 offset:17408
	ds_read_b128 v[196:199], v144 offset:18432
	ds_read_b128 v[200:203], v144 offset:19456
	ds_read_b128 v[204:207], v144 offset:20480
	ds_read_b128 v[208:211], v144 offset:21504
	ds_read_b128 v[212:215], v144 offset:22528
	ds_read_b128 v[216:219], v144 offset:23552
	global_load_lds_dwordx4 v[142:143], off
	s_add_i32 m0, s62, 0x2000
	s_add_u32 s62, s14, 0x80000
	v_lshl_add_u64 v[178:179], s[14:15], 0, v[136:137]
	s_addc_u32 s63, s15, 0
	s_add_i32 s64, s64, s27
	global_load_lds_dwordx4 v[178:179], off
	v_lshl_add_u64 v[184:185], s[62:63], 0, v[132:133]
	s_mov_b32 m0, s64
	v_lshl_add_u64 v[220:221], s[22:23], 0, v[134:135]
	global_load_lds_dwordx4 v[184:185], off
	v_lshl_add_u64 v[184:185], s[62:63], 0, v[136:137]
	s_add_i32 m0, s64, 0x2000
	s_nop 0
	global_load_lds_dwordx4 v[184:185], off
	v_lshl_add_u64 v[184:185], s[22:23], 0, v[130:131]
	s_mov_b32 m0, s19
	s_nop 0
	global_load_lds_dwordx4 v[184:185], off
	s_mov_b32 m0, s28
	s_nop 0
	global_load_lds_dwordx4 v[220:221], off
	s_waitcnt vmcnt(8)
	s_waitcnt lgkmcnt(0)
	s_barrier
; #define PG8_STAGE(bufoff, gbase, voff) do { _Pragma("unroll") for (int _i = 0; _i < 2; ++_i) \
;         __builtin_amdgcn_global_load_lds((const unsigned*)((const char*)(gbase) + (voff)[_i]), (LAS unsigned*)(lds + (bufoff) + ldsw + _i * 8192), 16, 0, 0); } while (0)
; #define PG8_LDA(dst, b, h) do { _Pragma("unroll") for (int m = 0; m < 4; ++m) _Pragma("unroll") for (int k = 0; k < 2; ++k) dst[m][k] = *(const LAS bf16x8*)(lds + PG8_SA(b, h) + aoff + m * 2048 + k * 1024); } while (0)
; #define PG8_LDB(dst, b, h) do { _Pragma("unroll") for (int n = 0; n < 2; ++n) _Pragma("unroll") for (int k = 0; k < 2; ++k) dst[n][k] = *(const LAS bf16x8*)(lds + PG8_SB(b, h) + boff + n * 2048 + k * 1024); } while (0)
; #define PG8_MMA(ai, bj, At, Bt) do { __builtin_amdgcn_s_setprio(1); _Pragma("unroll") for (int m = 0; m < 4; ++m) _Pragma("unroll") for (int n = 0; n < 2; ++n) _Pragma("unroll") for (int k = 0; k < 2; ++k) \
;         acc[ai][bj][m][n] = __builtin_amdgcn_mfma_f32_16x16x32_bf16(Bt[n][k], At[m][k], acc[ai][bj][m][n], 0, 0, 0); __builtin_amdgcn_s_setprio(0); } while (0)
; #define PG8_WAIT_V(n) asm volatile("s_waitcnt vmcnt(" #n ")" ::: "memory")
; #define PG8_WAIT_L(n) asm volatile("s_waitcnt lgkmcnt(" #n ")" ::: "memory")
; #define PG8_BAR __builtin_amdgcn_s_barrier()
; #define PG8_SCHED __builtin_amdgcn_sched_barrier(0)
; template <class Epi>
; __device__ __forceinline__ void gemm_phase(LAS unsigned char* lds, const Gemm g, const StaticOrder& S, const Epi& E) {
;     ...
;             PG8_WAIT_V(8); PG8_WAIT_L(0); PG8_BAR; PG8_MMA(1, 0, At, B0); PG8_MMA(1, 1, At, B1); PG8_BAR; PG8_SCHED;
;             PG8_LDB(B0, 1, 0); PG8_LDB(B1, 1, 1); PG8_SCHED; PG8_LDA(At, 1, 0); PG8_STAGE(PG8_SA(0, 1), a2 + hstepA, voffA);
;             PG8_WAIT_V(8); PG8_WAIT_L(0); PG8_BAR; PG8_MMA(0, 0, At, B0); PG8_MMA(0, 1, At, B1); PG8_BAR; PG8_SCHED;
;             PG8_LDA(At, 1, 1); PG8_STAGE(PG8_SB(1, 0), b3, voffB); PG8_STAGE(PG8_SB(1, 1), b3 + hstepB, voffB); PG8_STAGE(PG8_SA(1, 0), a3, voffA);
	s_setprio 1
	s_waitcnt lgkmcnt(0)
	v_mfma_f32_16x16x32_bf16 v[62:65], v[146:149], v[188:191], v[62:65]
	v_mfma_f32_16x16x32_bf16 v[58:61], v[154:157], v[188:191], v[58:61]
	v_mfma_f32_16x16x32_bf16 v[46:49], v[146:149], v[196:199], v[46:49]
	v_mfma_f32_16x16x32_bf16 v[42:45], v[154:157], v[196:199], v[42:45]
	v_mfma_f32_16x16x32_bf16 v[30:33], v[146:149], v[204:207], v[30:33]
	v_mfma_f32_16x16x32_bf16 v[26:29], v[154:157], v[204:207], v[26:29]
	v_mfma_f32_16x16x32_bf16 v[14:17], v[146:149], v[212:215], v[14:17]
	v_mfma_f32_16x16x32_bf16 v[10:13], v[154:157], v[212:215], v[10:13]
	v_mfma_f32_16x16x32_bf16 v[62:65], v[150:153], v[192:195], v[62:65]
	v_mfma_f32_16x16x32_bf16 v[58:61], v[158:161], v[192:195], v[58:61]
	v_mfma_f32_16x16x32_bf16 v[46:49], v[150:153], v[200:203], v[46:49]
	v_mfma_f32_16x16x32_bf16 v[42:45], v[158:161], v[200:203], v[42:45]
	v_mfma_f32_16x16x32_bf16 v[30:33], v[150:153], v[208:211], v[30:33]
	v_mfma_f32_16x16x32_bf16 v[26:29], v[158:161], v[208:211], v[26:29]
	v_mfma_f32_16x16x32_bf16 v[14:17], v[150:153], v[216:219], v[14:17]
	v_mfma_f32_16x16x32_bf16 v[10:13], v[158:161], v[216:219], v[10:13]
	s_setprio 0
	s_setprio 1
	v_mfma_f32_16x16x32_bf16 v[54:57], v[162:165], v[188:191], v[54:57]
	v_mfma_f32_16x16x32_bf16 v[50:53], v[170:173], v[188:191], v[50:53]
	v_mfma_f32_16x16x32_bf16 v[38:41], v[162:165], v[196:199], v[38:41]
	v_mfma_f32_16x16x32_bf16 v[34:37], v[170:173], v[196:199], v[34:37]
	v_mfma_f32_16x16x32_bf16 v[22:25], v[162:165], v[204:207], v[22:25]
	v_mfma_f32_16x16x32_bf16 v[18:21], v[170:173], v[204:207], v[18:21]
	v_mfma_f32_16x16x32_bf16 v[6:9], v[162:165], v[212:215], v[6:9]
	v_mfma_f32_16x16x32_bf16 v[2:5], v[170:173], v[212:215], v[2:5]
	v_mfma_f32_16x16x32_bf16 v[54:57], v[166:169], v[192:195], v[54:57]
	v_mfma_f32_16x16x32_bf16 v[50:53], v[174:177], v[192:195], v[50:53]
	v_mfma_f32_16x16x32_bf16 v[38:41], v[166:169], v[200:203], v[38:41]
	v_mfma_f32_16x16x32_bf16 v[34:37], v[174:177], v[200:203], v[34:37]
	v_mfma_f32_16x16x32_bf16 v[22:25], v[166:169], v[208:211], v[22:25]
	v_mfma_f32_16x16x32_bf16 v[18:21], v[174:177], v[208:211], v[18:21]
	v_mfma_f32_16x16x32_bf16 v[6:9], v[166:169], v[216:219], v[6:9]
	v_mfma_f32_16x16x32_bf16 v[2:5], v[174:177], v[216:219], v[2:5]
	s_setprio 0
	s_barrier
	s_add_i32 s62, 0, 0x18000
	v_add_u32_e32 v145, s62, v1
	s_add_i32 s63, 0, 0x1c000
	ds_read_b128 v[146:149], v145
	ds_read_b128 v[150:153], v145 offset:1024
	ds_read_b128 v[154:157], v145 offset:2048
	ds_read_b128 v[158:161], v145 offset:3072
	v_add_u32_e32 v145, s63, v1
	ds_read_b128 v[162:165], v145
	ds_read_b128 v[166:169], v145 offset:1024
	ds_read_b128 v[170:173], v145 offset:2048
	ds_read_b128 v[174:177], v145 offset:3072
	s_add_u32 s22, s22, 0x80000
	s_addc_u32 s23, s23, 0
	s_mov_b32 m0, s29
	v_lshl_add_u64 v[222:223], s[22:23], 0, v[130:131]
	ds_read_b128 v[188:191], v144 offset:32768
	ds_read_b128 v[192:195], v144 offset:33792
	ds_read_b128 v[196:199], v144 offset:34816
	ds_read_b128 v[200:203], v144 offset:35840
	ds_read_b128 v[204:207], v144 offset:36864
	ds_read_b128 v[208:211], v144 offset:37888
	ds_read_b128 v[212:215], v144 offset:38912
	ds_read_b128 v[216:219], v144 offset:39936
	global_load_lds_dwordx4 v[222:223], off
	v_lshl_add_u64 v[222:223], s[22:23], 0, v[134:135]
	s_mov_b32 m0, s30
	s_nop 0
	global_load_lds_dwordx4 v[222:223], off
	s_waitcnt vmcnt(8)
	s_waitcnt lgkmcnt(0)
	s_barrier
	s_setprio 1
	s_waitcnt lgkmcnt(0)
	v_mfma_f32_16x16x32_bf16 v[126:129], v[146:149], v[188:191], v[126:129]
	v_mfma_f32_16x16x32_bf16 v[122:125], v[154:157], v[188:191], v[122:125]
	v_mfma_f32_16x16x32_bf16 v[110:113], v[146:149], v[196:199], v[110:113]
	v_mfma_f32_16x16x32_bf16 v[106:109], v[154:157], v[196:199], v[106:109]
	v_mfma_f32_16x16x32_bf16 v[94:97], v[146:149], v[204:207], v[94:97]
	v_mfma_f32_16x16x32_bf16 v[90:93], v[154:157], v[204:207], v[90:93]
	v_mfma_f32_16x16x32_bf16 v[78:81], v[146:149], v[212:215], v[78:81]
	v_mfma_f32_16x16x32_bf16 v[74:77], v[154:157], v[212:215], v[74:77]
	v_mfma_f32_16x16x32_bf16 v[126:129], v[150:153], v[192:195], v[126:129]
	v_mfma_f32_16x16x32_bf16 v[122:125], v[158:161], v[192:195], v[122:125]
	v_mfma_f32_16x16x32_bf16 v[110:113], v[150:153], v[200:203], v[110:113]
	v_mfma_f32_16x16x32_bf16 v[106:109], v[158:161], v[200:203], v[106:109]
	v_mfma_f32_16x16x32_bf16 v[94:97], v[150:153], v[208:211], v[94:97]
	v_mfma_f32_16x16x32_bf16 v[90:93], v[158:161], v[208:211], v[90:93]
	v_mfma_f32_16x16x32_bf16 v[78:81], v[150:153], v[216:219], v[78:81]
	v_mfma_f32_16x16x32_bf16 v[74:77], v[158:161], v[216:219], v[74:77]
	s_setprio 0
	s_setprio 1
	v_mfma_f32_16x16x32_bf16 v[118:121], v[162:165], v[188:191], v[118:121]
	v_mfma_f32_16x16x32_bf16 v[114:117], v[170:173], v[188:191], v[114:117]
	v_mfma_f32_16x16x32_bf16 v[102:105], v[162:165], v[196:199], v[102:105]
	v_mfma_f32_16x16x32_bf16 v[98:101], v[170:173], v[196:199], v[98:101]
	v_mfma_f32_16x16x32_bf16 v[86:89], v[162:165], v[204:207], v[86:89]
	v_mfma_f32_16x16x32_bf16 v[82:85], v[170:173], v[204:207], v[82:85]
	v_mfma_f32_16x16x32_bf16 v[70:73], v[162:165], v[212:215], v[70:73]
	v_mfma_f32_16x16x32_bf16 v[66:69], v[170:173], v[212:215], v[66:69]
	v_mfma_f32_16x16x32_bf16 v[118:121], v[166:169], v[192:195], v[118:121]
	v_mfma_f32_16x16x32_bf16 v[114:117], v[174:177], v[192:195], v[114:117]
	v_mfma_f32_16x16x32_bf16 v[102:105], v[166:169], v[200:203], v[102:105]
	v_mfma_f32_16x16x32_bf16 v[98:101], v[174:177], v[200:203], v[98:101]
	v_mfma_f32_16x16x32_bf16 v[86:89], v[166:169], v[208:211], v[86:89]
	v_mfma_f32_16x16x32_bf16 v[82:85], v[174:177], v[208:211], v[82:85]
	v_mfma_f32_16x16x32_bf16 v[70:73], v[166:169], v[216:219], v[70:73]
	v_mfma_f32_16x16x32_bf16 v[66:69], v[174:177], v[216:219], v[66:69]
	s_setprio 0
	s_barrier
; #define PG8_STAGE(bufoff, gbase, voff) do { _Pragma("unroll") for (int _i = 0; _i < 2; ++_i) \
;         __builtin_amdgcn_global_load_lds((const unsigned*)((const char*)(gbase) + (voff)[_i]), (LAS unsigned*)(lds + (bufoff) + ldsw + _i * 8192), 16, 0, 0); } while (0)
; #define PG8_LDA(dst, b, h) do { _Pragma("unroll") for (int m = 0; m < 4; ++m) _Pragma("unroll") for (int k = 0; k < 2; ++k) dst[m][k] = *(const LAS bf16x8*)(lds + PG8_SA(b, h) + aoff + m * 2048 + k * 1024); } while (0)
; #define PG8_LDB(dst, b, h) do { _Pragma("unroll") for (int n = 0; n < 2; ++n) _Pragma("unroll") for (int k = 0; k < 2; ++k) dst[n][k] = *(const LAS bf16x8*)(lds + PG8_SB(b, h) + boff + n * 2048 + k * 1024); } while (0)
; #define PG8_MMA(ai, bj, At, Bt) do { __builtin_amdgcn_s_setprio(1); _Pragma("unroll") for (int m = 0; m < 4; ++m) _Pragma("unroll") for (int n = 0; n < 2; ++n) _Pragma("unroll") for (int k = 0; k < 2; ++k) \
;         acc[ai][bj][m][n] = __builtin_amdgcn_mfma_f32_16x16x32_bf16(Bt[n][k], At[m][k], acc[ai][bj][m][n], 0, 0, 0); __builtin_amdgcn_s_setprio(0); } while (0)
; #define PG8_WAIT_V(n) asm volatile("s_waitcnt vmcnt(" #n ")" ::: "memory")
; #define PG8_BAR __builtin_amdgcn_s_barrier()
; template <class Epi>
; __device__ __forceinline__ void gemm_phase(LAS unsigned char* lds, const Gemm g, const StaticOrder& S, const Epi& E) {
;     ...
;             PG8_LDB(B0, 0, 0); PG8_LDB(B1, 0, 1); PG8_SCHED; PG8_LDA(At, 0, 0); PG8_STAGE(PG8_SA(1, 1), a1 + hstepA, voffA);
;             PG8_WAIT_V(8); PG8_WAIT_L(0); PG8_BAR; PG8_MMA(0, 0, At, B0); PG8_MMA(0, 1, At, B1); PG8_BAR; PG8_SCHED;
;             PG8_LDA(At, 0, 1); PG8_STAGE(PG8_SB(0, 0), b2, voffB); PG8_STAGE(PG8_SB(0, 1), b2 + hstepB, voffB); PG8_STAGE(PG8_SA(0, 0), a2, voffA);
;             PG8_WAIT_V(8); PG8_WAIT_L(0); PG8_BAR; PG8_MMA(1, 0, At, B0); PG8_MMA(1, 1, At, B1); PG8_BAR; PG8_SCHED;
;             PG8_LDB(B0, 1, 0); PG8_LDB(B1, 1, 1); PG8_SCHED; PG8_LDA(At, 1, 0); PG8_STAGE(PG8_SA(0, 1), a2 + hstepA, voffA);
;             PG8_WAIT_V(8); PG8_WAIT_L(0); PG8_BAR; PG8_MMA(0, 0, At, B0); PG8_MMA(0, 1, At, B1); PG8_BAR; PG8_SCHED;
;             PG8_LDA(At, 1, 1); PG8_STAGE(PG8_SB(1, 0), b3, voffB); PG8_STAGE(PG8_SB(1, 1), b3 + hstepB, voffB); PG8_STAGE(PG8_SA(1, 0), a3, voffA);
;             PG8_WAIT_V(8); PG8_WAIT_L(0); PG8_BAR; PG8_MMA(1, 0, At, B0); PG8_MMA(1, 1, At, B1); PG8_BAR; PG8_SCHED;
;         }
	s_add_i32 s22, s62, s27
	v_lshl_add_u64 v[142:143], v[142:143], 0, s[84:85]
	s_mov_b32 m0, s22
	ds_read_b128 v[188:191], v144 offset:49152
	ds_read_b128 v[192:195], v144 offset:50176
	ds_read_b128 v[196:199], v144 offset:51200
	ds_read_b128 v[200:203], v144 offset:52224
	ds_read_b128 v[204:207], v144 offset:53248
	ds_read_b128 v[208:211], v144 offset:54272
	ds_read_b128 v[212:215], v144 offset:55296
	ds_read_b128 v[216:219], v144 offset:56320
	global_load_lds_dwordx4 v[142:143], off
	s_add_i32 m0, s22, 0x2000
	s_add_u32 s14, s14, 0x80080
	v_lshl_add_u64 v[142:143], v[178:179], 0, s[84:85]
	s_addc_u32 s15, s15, 0
	s_add_i32 s22, s63, s27
	global_load_lds_dwordx4 v[142:143], off
	v_lshl_add_u64 v[142:143], s[14:15], 0, v[132:133]
	s_mov_b32 m0, s22
	s_nop 0
	global_load_lds_dwordx4 v[142:143], off
	v_lshl_add_u64 v[142:143], s[14:15], 0, v[136:137]
	s_add_i32 m0, s22, 0x2000
	s_nop 0
	global_load_lds_dwordx4 v[142:143], off
	v_lshl_add_u64 v[142:143], v[184:185], 0, s[84:85]
	s_mov_b32 m0, s34
	s_nop 0
	global_load_lds_dwordx4 v[142:143], off
	v_lshl_add_u64 v[142:143], v[220:221], 0, s[84:85]
	s_mov_b32 m0, s35
	s_nop 0
	global_load_lds_dwordx4 v[142:143], off
	s_waitcnt vmcnt(8)
	s_waitcnt lgkmcnt(0)
	s_barrier
	s_setprio 1
	s_waitcnt lgkmcnt(0)
	v_mfma_f32_16x16x32_bf16 v[62:65], v[146:149], v[188:191], v[62:65]
	v_mfma_f32_16x16x32_bf16 v[58:61], v[154:157], v[188:191], v[58:61]
	v_mfma_f32_16x16x32_bf16 v[46:49], v[146:149], v[196:199], v[46:49]
	v_mfma_f32_16x16x32_bf16 v[42:45], v[154:157], v[196:199], v[42:45]
	v_mfma_f32_16x16x32_bf16 v[30:33], v[146:149], v[204:207], v[30:33]
	v_mfma_f32_16x16x32_bf16 v[26:29], v[154:157], v[204:207], v[26:29]
	v_mfma_f32_16x16x32_bf16 v[14:17], v[146:149], v[212:215], v[14:17]
	v_mfma_f32_16x16x32_bf16 v[10:13], v[154:157], v[212:215], v[10:13]
	v_mfma_f32_16x16x32_bf16 v[62:65], v[150:153], v[192:195], v[62:65]
	v_mfma_f32_16x16x32_bf16 v[58:61], v[158:161], v[192:195], v[58:61]
	v_mfma_f32_16x16x32_bf16 v[46:49], v[150:153], v[200:203], v[46:49]
	v_mfma_f32_16x16x32_bf16 v[42:45], v[158:161], v[200:203], v[42:45]
	v_mfma_f32_16x16x32_bf16 v[30:33], v[150:153], v[208:211], v[30:33]
	v_mfma_f32_16x16x32_bf16 v[26:29], v[158:161], v[208:211], v[26:29]
	v_mfma_f32_16x16x32_bf16 v[14:17], v[150:153], v[216:219], v[14:17]
	v_mfma_f32_16x16x32_bf16 v[10:13], v[158:161], v[216:219], v[10:13]
	s_setprio 0
	s_setprio 1
	v_mfma_f32_16x16x32_bf16 v[54:57], v[162:165], v[188:191], v[54:57]
	v_mfma_f32_16x16x32_bf16 v[50:53], v[170:173], v[188:191], v[50:53]
	v_mfma_f32_16x16x32_bf16 v[38:41], v[162:165], v[196:199], v[38:41]
	v_mfma_f32_16x16x32_bf16 v[34:37], v[170:173], v[196:199], v[34:37]
	v_mfma_f32_16x16x32_bf16 v[22:25], v[162:165], v[204:207], v[22:25]
	v_mfma_f32_16x16x32_bf16 v[18:21], v[170:173], v[204:207], v[18:21]
	v_mfma_f32_16x16x32_bf16 v[6:9], v[162:165], v[212:215], v[6:9]
	v_mfma_f32_16x16x32_bf16 v[2:5], v[170:173], v[212:215], v[2:5]
	v_mfma_f32_16x16x32_bf16 v[54:57], v[166:169], v[192:195], v[54:57]
	v_mfma_f32_16x16x32_bf16 v[50:53], v[174:177], v[192:195], v[50:53]
	v_mfma_f32_16x16x32_bf16 v[38:41], v[166:169], v[200:203], v[38:41]
	v_mfma_f32_16x16x32_bf16 v[34:37], v[174:177], v[200:203], v[34:37]
	v_mfma_f32_16x16x32_bf16 v[22:25], v[166:169], v[208:211], v[22:25]
	v_mfma_f32_16x16x32_bf16 v[18:21], v[174:177], v[208:211], v[18:21]
	v_mfma_f32_16x16x32_bf16 v[6:9], v[166:169], v[216:219], v[6:9]
	v_mfma_f32_16x16x32_bf16 v[2:5], v[174:177], v[216:219], v[2:5]
	s_setprio 0
	s_barrier
	s_add_i32 s41, s41, 2
	s_add_u32 s20, s20, 0x100
	s_addc_u32 s21, s21, 0
	s_add_u32 s52, s52, 0x100
	s_addc_u32 s53, s53, 0
	s_cmp_gt_u32 s41, 29
	s_cbranch_scc0 .LBB0_2130
	s_cmp_ge_u32 s74, 32
	s_cbranch_scc1 .Lwpf_d
	s_lshl_b32 s100, s74, 9
	v_add_u32_e32 v146, s100, v246
	v_lshrrev_b32_e32 v147, 3, v146
	v_and_b32_e32 v146, 7, v146
	v_lshlrev_b32_e32 v146, 7, v146
	v_lshl_add_u32 v146, v147, 14, v146
	s_add_u32 s100, s88, 0x2000000
	s_addc_u32 s101, s89, 0
	s_mov_b32 m0, 0x21000
	s_nop 0
	global_load_lds_dword v146, s[100:101]

; #define PG8_STAGE(bufoff, gbase, voff) do { _Pragma("unroll") for (int _i = 0; _i < 2; ++_i) \
;         __builtin_amdgcn_global_load_lds((const unsigned*)((const char*)(gbase) + (voff)[_i]), (LAS unsigned*)(lds + (bufoff) + ldsw + _i * 8192), 16, 0, 0); } while (0)
; #define PG8_LDA(dst, b, h) do { _Pragma("unroll") for (int m = 0; m < 4; ++m) _Pragma("unroll") for (int k = 0; k < 2; ++k) dst[m][k] = *(const LAS bf16x8*)(lds + PG8_SA(b, h) + aoff + m * 2048 + k * 1024); } while (0)
; #define PG8_LDB(dst, b, h) do { _Pragma("unroll") for (int n = 0; n < 2; ++n) _Pragma("unroll") for (int k = 0; k < 2; ++k) dst[n][k] = *(const LAS bf16x8*)(lds + PG8_SB(b, h) + boff + n * 2048 + k * 1024); } while (0)
; #define PG8_MMA(ai, bj, At, Bt) do { __builtin_amdgcn_s_setprio(1); _Pragma("unroll") for (int m = 0; m < 4; ++m) _Pragma("unroll") for (int n = 0; n < 2; ++n) _Pragma("unroll") for (int k = 0; k < 2; ++k) \
;         acc[ai][bj][m][n] = __builtin_amdgcn_mfma_f32_16x16x32_bf16(Bt[n][k], At[m][k], acc[ai][bj][m][n], 0, 0, 0); __builtin_amdgcn_s_setprio(0); } while (0)
; #define PG8_WAIT_V(n) asm volatile("s_waitcnt vmcnt(" #n ")" ::: "memory")
; #define PG8_WAIT_L(n) asm volatile("s_waitcnt lgkmcnt(" #n ")" ::: "memory")
; #define PG8_BAR __builtin_amdgcn_s_barrier()
; #define PG8_SCHED __builtin_amdgcn_sched_barrier(0)
; template <class Epi>
; __device__ __forceinline__ void gemm_phase(LAS unsigned char* lds, const Gemm g, const StaticOrder& S, const Epi& E) {
;     ...
;             PG8_LDB(B0, 0, 0); PG8_LDB(B1, 0, 1); PG8_SCHED; PG8_LDA(At, 0, 0); PG8_STAGE(PG8_SA(1, 1), a1 + hstepA, voffA);
;             PG8_WAIT_V(8); PG8_WAIT_L(0); PG8_BAR; PG8_MMA(0, 0, At, B0); PG8_MMA(0, 1, At, B1); PG8_BAR; PG8_SCHED;
;             PG8_LDA(At, 0, 1); PG8_STAGE(PG8_SB(0, 0), b2, voffB); PG8_STAGE(PG8_SB(0, 1), b2 + hstepB, voffB); PG8_STAGE(PG8_SA(0, 0), a2, voffA);
;             PG8_WAIT_V(8); PG8_WAIT_L(0); PG8_BAR; PG8_MMA(1, 0, At, B0); PG8_MMA(1, 1, At, B1); PG8_BAR; PG8_SCHED;
;             PG8_LDB(B0, 1, 0); PG8_LDB(B1, 1, 1); PG8_SCHED; PG8_LDA(At, 1, 0); PG8_STAGE(PG8_SA(0, 1), a2 + hstepA, voffA);
;             PG8_WAIT_V(8); PG8_WAIT_L(0); PG8_BAR; PG8_MMA(0, 0, At, B0); PG8_MMA(0, 1, At, B1); PG8_BAR; PG8_SCHED;
.LBB0_2233:
	s_add_u32 s14, s24, 0xffe00080
	s_addc_u32 s15, s25, -1
	s_add_i32 s52, 0, 0x10000
	s_cmpk_eq_i32 s41, 0x7c
	s_cselect_b32 s27, s1, s15
	s_cselect_b32 s26, s3, s14
	s_cselect_b32 s15, s9, s40
	s_cselect_b32 s14, s17, s19
	s_add_i32 s62, 0, 0x14000
	v_add_u32_e32 v142, s52, v1
	v_add_u32_e32 v167, s62, v1
	ds_read_b128 v[130:133], v142
	ds_read_b128 v[134:137], v142 offset:1024
	ds_read_b128 v[138:141], v142 offset:2048
	ds_read_b128 v[142:145], v142 offset:3072
	ds_read_b128 v[146:149], v167
	ds_read_b128 v[162:165], v167 offset:1024
	ds_read_b128 v[168:171], v167 offset:2048
	ds_read_b128 v[172:175], v167 offset:3072
	v_lshl_add_u64 v[184:185], s[24:25], 0, v[158:159]
	s_add_i32 m0, s31, 0xc000
	ds_read_b128 v[176:179], v166
	ds_read_b128 v[188:191], v166 offset:1024
	ds_read_b128 v[192:195], v166 offset:2048
	ds_read_b128 v[196:199], v166 offset:3072
	ds_read_b128 v[200:203], v166 offset:4096
	ds_read_b128 v[204:207], v166 offset:5120
	ds_read_b128 v[208:211], v166 offset:6144
	ds_read_b128 v[212:215], v166 offset:7168
	global_load_lds_dwordx4 v[184:185], off
	v_lshl_add_u64 v[184:185], s[24:25], 0, v[160:161]
	s_add_i32 m0, s31, 0xe000
	s_nop 0
	global_load_lds_dwordx4 v[184:185], off
	s_waitcnt vmcnt(8)
	s_waitcnt lgkmcnt(0)
	s_barrier
	s_setprio 1
	s_waitcnt lgkmcnt(0)
	v_mfma_f32_16x16x32_bf16 v[126:129], v[130:133], v[176:179], v[126:129]
	v_mfma_f32_16x16x32_bf16 v[122:125], v[138:141], v[176:179], v[122:125]
	v_mfma_f32_16x16x32_bf16 v[118:121], v[130:133], v[192:195], v[118:121]
	v_mfma_f32_16x16x32_bf16 v[114:117], v[138:141], v[192:195], v[114:117]
	v_mfma_f32_16x16x32_bf16 v[94:97], v[130:133], v[200:203], v[94:97]
	v_mfma_f32_16x16x32_bf16 v[90:93], v[138:141], v[200:203], v[90:93]
	v_mfma_f32_16x16x32_bf16 v[82:85], v[130:133], v[208:211], v[82:85]
	v_mfma_f32_16x16x32_bf16 v[74:77], v[138:141], v[208:211], v[74:77]
	v_mfma_f32_16x16x32_bf16 v[126:129], v[134:137], v[188:191], v[126:129]
	v_mfma_f32_16x16x32_bf16 v[122:125], v[142:145], v[188:191], v[122:125]
	v_mfma_f32_16x16x32_bf16 v[118:121], v[134:137], v[196:199], v[118:121]
	v_mfma_f32_16x16x32_bf16 v[114:117], v[142:145], v[196:199], v[114:117]
	v_mfma_f32_16x16x32_bf16 v[94:97], v[134:137], v[204:207], v[94:97]
	v_mfma_f32_16x16x32_bf16 v[90:93], v[142:145], v[204:207], v[90:93]
	v_mfma_f32_16x16x32_bf16 v[82:85], v[134:137], v[212:215], v[82:85]
	v_mfma_f32_16x16x32_bf16 v[74:77], v[142:145], v[212:215], v[74:77]
	s_setprio 0
	s_setprio 1
	v_mfma_f32_16x16x32_bf16 v[110:113], v[146:149], v[176:179], v[110:113]
	v_mfma_f32_16x16x32_bf16 v[106:109], v[168:171], v[176:179], v[106:109]
	v_mfma_f32_16x16x32_bf16 v[102:105], v[146:149], v[192:195], v[102:105]
	v_mfma_f32_16x16x32_bf16 v[98:101], v[168:171], v[192:195], v[98:101]
	v_mfma_f32_16x16x32_bf16 v[86:89], v[146:149], v[200:203], v[86:89]
	v_mfma_f32_16x16x32_bf16 v[78:81], v[168:171], v[200:203], v[78:81]
	v_mfma_f32_16x16x32_bf16 v[70:73], v[146:149], v[208:211], v[70:73]
	v_mfma_f32_16x16x32_bf16 v[66:69], v[168:171], v[208:211], v[66:69]
	v_mfma_f32_16x16x32_bf16 v[110:113], v[162:165], v[188:191], v[110:113]
	v_mfma_f32_16x16x32_bf16 v[106:109], v[172:175], v[188:191], v[106:109]
	v_mfma_f32_16x16x32_bf16 v[102:105], v[162:165], v[196:199], v[102:105]
	v_mfma_f32_16x16x32_bf16 v[98:101], v[172:175], v[196:199], v[98:101]
	v_mfma_f32_16x16x32_bf16 v[86:89], v[162:165], v[204:207], v[86:89]
	v_mfma_f32_16x16x32_bf16 v[78:81], v[172:175], v[204:207], v[78:81]
	v_mfma_f32_16x16x32_bf16 v[70:73], v[162:165], v[212:215], v[70:73]
	v_mfma_f32_16x16x32_bf16 v[66:69], v[172:175], v[212:215], v[66:69]
	s_setprio 0
	s_barrier
	s_add_i32 s52, s52, s30
	v_lshl_add_u64 v[184:185], s[14:15], 0, v[152:153]
	s_mov_b32 m0, s52
	ds_read_b128 v[176:179], v166 offset:16384
	ds_read_b128 v[188:191], v166 offset:17408
	ds_read_b128 v[192:195], v166 offset:18432
	ds_read_b128 v[196:199], v166 offset:19456
	ds_read_b128 v[200:203], v166 offset:20480
	ds_read_b128 v[204:207], v166 offset:21504
	ds_read_b128 v[208:211], v166 offset:22528
	ds_read_b128 v[212:215], v166 offset:23552
	global_load_lds_dwordx4 v[184:185], off
	s_add_i32 m0, s52, 0x2000
	s_add_u32 s52, s14, 0x200000
	v_lshl_add_u64 v[216:217], s[14:15], 0, v[156:157]
	s_addc_u32 s53, s15, 0
	s_add_i32 s62, s62, s30
	global_load_lds_dwordx4 v[216:217], off
	v_lshl_add_u64 v[218:219], s[52:53], 0, v[152:153]
	s_mov_b32 m0, s62
	v_lshl_add_u64 v[220:221], s[26:27], 0, v[154:155]
	global_load_lds_dwordx4 v[218:219], off
	v_lshl_add_u64 v[218:219], s[52:53], 0, v[156:157]
	s_add_i32 m0, s62, 0x2000
	s_nop 0
	global_load_lds_dwordx4 v[218:219], off
	v_lshl_add_u64 v[218:219], s[26:27], 0, v[150:151]
	s_mov_b32 m0, s31
	s_nop 0
	global_load_lds_dwordx4 v[218:219], off
	s_mov_b32 m0, s34
	s_nop 0
	global_load_lds_dwordx4 v[220:221], off
	s_waitcnt vmcnt(8)
	s_waitcnt lgkmcnt(0)
	s_barrier
; #define PG8_STAGE(bufoff, gbase, voff) do { _Pragma("unroll") for (int _i = 0; _i < 2; ++_i) \
;         __builtin_amdgcn_global_load_lds((const unsigned*)((const char*)(gbase) + (voff)[_i]), (LAS unsigned*)(lds + (bufoff) + ldsw + _i * 8192), 16, 0, 0); } while (0)
; #define PG8_LDA(dst, b, h) do { _Pragma("unroll") for (int m = 0; m < 4; ++m) _Pragma("unroll") for (int k = 0; k < 2; ++k) dst[m][k] = *(const LAS bf16x8*)(lds + PG8_SA(b, h) + aoff + m * 2048 + k * 1024); } while (0)
; #define PG8_LDB(dst, b, h) do { _Pragma("unroll") for (int n = 0; n < 2; ++n) _Pragma("unroll") for (int k = 0; k < 2; ++k) dst[n][k] = *(const LAS bf16x8*)(lds + PG8_SB(b, h) + boff + n * 2048 + k * 1024); } while (0)
; #define PG8_MMA(ai, bj, At, Bt) do { __builtin_amdgcn_s_setprio(1); _Pragma("unroll") for (int m = 0; m < 4; ++m) _Pragma("unroll") for (int n = 0; n < 2; ++n) _Pragma("unroll") for (int k = 0; k < 2; ++k) \
;         acc[ai][bj][m][n] = __builtin_amdgcn_mfma_f32_16x16x32_bf16(Bt[n][k], At[m][k], acc[ai][bj][m][n], 0, 0, 0); __builtin_amdgcn_s_setprio(0); } while (0)
; #define PG8_WAIT_V(n) asm volatile("s_waitcnt vmcnt(" #n ")" ::: "memory")
; #define PG8_WAIT_L(n) asm volatile("s_waitcnt lgkmcnt(" #n ")" ::: "memory")
; #define PG8_BAR __builtin_amdgcn_s_barrier()
; #define PG8_SCHED __builtin_amdgcn_sched_barrier(0)
; template <class Epi>
; __device__ __forceinline__ void gemm_phase(LAS unsigned char* lds, const Gemm g, const StaticOrder& S, const Epi& E) {
;     ...
;             PG8_WAIT_V(8); PG8_WAIT_L(0); PG8_BAR; PG8_MMA(1, 0, At, B0); PG8_MMA(1, 1, At, B1); PG8_BAR; PG8_SCHED;
;             PG8_LDB(B0, 1, 0); PG8_LDB(B1, 1, 1); PG8_SCHED; PG8_LDA(At, 1, 0); PG8_STAGE(PG8_SA(0, 1), a2 + hstepA, voffA);
;             PG8_WAIT_V(8); PG8_WAIT_L(0); PG8_BAR; PG8_MMA(0, 0, At, B0); PG8_MMA(0, 1, At, B1); PG8_BAR; PG8_SCHED;
;             PG8_LDA(At, 1, 1); PG8_STAGE(PG8_SB(1, 0), b3, voffB); PG8_STAGE(PG8_SB(1, 1), b3 + hstepB, voffB); PG8_STAGE(PG8_SA(1, 0), a3, voffA);
	s_setprio 1
	s_waitcnt lgkmcnt(0)
	v_mfma_f32_16x16x32_bf16 v[62:65], v[130:133], v[176:179], v[62:65]
	v_mfma_f32_16x16x32_bf16 v[58:61], v[138:141], v[176:179], v[58:61]
	v_mfma_f32_16x16x32_bf16 v[50:53], v[130:133], v[192:195], v[50:53]
	v_mfma_f32_16x16x32_bf16 v[42:45], v[138:141], v[192:195], v[42:45]
	v_mfma_f32_16x16x32_bf16 v[30:33], v[130:133], v[200:203], v[30:33]
	v_mfma_f32_16x16x32_bf16 v[26:29], v[138:141], v[200:203], v[26:29]
	v_mfma_f32_16x16x32_bf16 v[18:21], v[130:133], v[208:211], v[18:21]
	v_mfma_f32_16x16x32_bf16 v[10:13], v[138:141], v[208:211], v[10:13]
	v_mfma_f32_16x16x32_bf16 v[62:65], v[134:137], v[188:191], v[62:65]
	v_mfma_f32_16x16x32_bf16 v[58:61], v[142:145], v[188:191], v[58:61]
	v_mfma_f32_16x16x32_bf16 v[50:53], v[134:137], v[196:199], v[50:53]
	v_mfma_f32_16x16x32_bf16 v[42:45], v[142:145], v[196:199], v[42:45]
	v_mfma_f32_16x16x32_bf16 v[30:33], v[134:137], v[204:207], v[30:33]
	v_mfma_f32_16x16x32_bf16 v[26:29], v[142:145], v[204:207], v[26:29]
	v_mfma_f32_16x16x32_bf16 v[18:21], v[134:137], v[212:215], v[18:21]
	v_mfma_f32_16x16x32_bf16 v[10:13], v[142:145], v[212:215], v[10:13]
	s_setprio 0
	s_setprio 1
	v_mfma_f32_16x16x32_bf16 v[54:57], v[146:149], v[176:179], v[54:57]
	v_mfma_f32_16x16x32_bf16 v[46:49], v[168:171], v[176:179], v[46:49]
	v_mfma_f32_16x16x32_bf16 v[38:41], v[146:149], v[192:195], v[38:41]
	v_mfma_f32_16x16x32_bf16 v[34:37], v[168:171], v[192:195], v[34:37]
	v_mfma_f32_16x16x32_bf16 v[22:25], v[146:149], v[200:203], v[22:25]
	v_mfma_f32_16x16x32_bf16 v[14:17], v[168:171], v[200:203], v[14:17]
	v_mfma_f32_16x16x32_bf16 v[6:9], v[146:149], v[208:211], v[6:9]
	v_mfma_f32_16x16x32_bf16 v[2:5], v[168:171], v[208:211], v[2:5]
	v_mfma_f32_16x16x32_bf16 v[54:57], v[162:165], v[188:191], v[54:57]
	v_mfma_f32_16x16x32_bf16 v[46:49], v[172:175], v[188:191], v[46:49]
	v_mfma_f32_16x16x32_bf16 v[38:41], v[162:165], v[196:199], v[38:41]
	v_mfma_f32_16x16x32_bf16 v[34:37], v[172:175], v[196:199], v[34:37]
	v_mfma_f32_16x16x32_bf16 v[22:25], v[162:165], v[204:207], v[22:25]
	v_mfma_f32_16x16x32_bf16 v[14:17], v[172:175], v[204:207], v[14:17]
	v_mfma_f32_16x16x32_bf16 v[6:9], v[162:165], v[212:215], v[6:9]
	v_mfma_f32_16x16x32_bf16 v[2:5], v[172:175], v[212:215], v[2:5]
	s_setprio 0
	s_barrier
	s_add_i32 s52, 0, 0x18000
	s_add_i32 s53, 0, 0x1c000
	v_add_u32_e32 v142, s52, v1
	v_add_u32_e32 v167, s53, v1
	ds_read_b128 v[130:133], v142
	ds_read_b128 v[134:137], v142 offset:1024
	ds_read_b128 v[138:141], v142 offset:2048
	ds_read_b128 v[142:145], v142 offset:3072
	ds_read_b128 v[146:149], v167
	ds_read_b128 v[162:165], v167 offset:1024
	ds_read_b128 v[168:171], v167 offset:2048
	ds_read_b128 v[172:175], v167 offset:3072
	s_add_u32 s26, s26, 0x200000
	s_addc_u32 s27, s27, 0
	s_mov_b32 m0, s35
	v_lshl_add_u64 v[222:223], s[26:27], 0, v[150:151]
	ds_read_b128 v[176:179], v166 offset:32768
	ds_read_b128 v[188:191], v166 offset:33792
	ds_read_b128 v[192:195], v166 offset:34816
	ds_read_b128 v[196:199], v166 offset:35840
	ds_read_b128 v[200:203], v166 offset:36864
	ds_read_b128 v[204:207], v166 offset:37888
	ds_read_b128 v[208:211], v166 offset:38912
	ds_read_b128 v[212:215], v166 offset:39936
	global_load_lds_dwordx4 v[222:223], off
	v_lshl_add_u64 v[222:223], s[26:27], 0, v[154:155]
	s_mov_b32 m0, s42
	s_nop 0
	global_load_lds_dwordx4 v[222:223], off
	s_waitcnt vmcnt(8)
	s_waitcnt lgkmcnt(0)
	s_barrier
	s_setprio 1
	s_waitcnt lgkmcnt(0)
	v_mfma_f32_16x16x32_bf16 v[126:129], v[130:133], v[176:179], v[126:129]
	v_mfma_f32_16x16x32_bf16 v[122:125], v[138:141], v[176:179], v[122:125]
	v_mfma_f32_16x16x32_bf16 v[118:121], v[130:133], v[192:195], v[118:121]
	v_mfma_f32_16x16x32_bf16 v[114:117], v[138:141], v[192:195], v[114:117]
	v_mfma_f32_16x16x32_bf16 v[94:97], v[130:133], v[200:203], v[94:97]
	v_mfma_f32_16x16x32_bf16 v[90:93], v[138:141], v[200:203], v[90:93]
	v_mfma_f32_16x16x32_bf16 v[82:85], v[130:133], v[208:211], v[82:85]
	v_mfma_f32_16x16x32_bf16 v[74:77], v[138:141], v[208:211], v[74:77]
	v_mfma_f32_16x16x32_bf16 v[126:129], v[134:137], v[188:191], v[126:129]
	v_mfma_f32_16x16x32_bf16 v[122:125], v[142:145], v[188:191], v[122:125]
	v_mfma_f32_16x16x32_bf16 v[118:121], v[134:137], v[196:199], v[118:121]
	v_mfma_f32_16x16x32_bf16 v[114:117], v[142:145], v[196:199], v[114:117]
	v_mfma_f32_16x16x32_bf16 v[94:97], v[134:137], v[204:207], v[94:97]
	v_mfma_f32_16x16x32_bf16 v[90:93], v[142:145], v[204:207], v[90:93]
	v_mfma_f32_16x16x32_bf16 v[82:85], v[134:137], v[212:215], v[82:85]
	v_mfma_f32_16x16x32_bf16 v[74:77], v[142:145], v[212:215], v[74:77]
	s_setprio 0
	s_setprio 1
	v_mfma_f32_16x16x32_bf16 v[110:113], v[146:149], v[176:179], v[110:113]
	v_mfma_f32_16x16x32_bf16 v[106:109], v[168:171], v[176:179], v[106:109]
	v_mfma_f32_16x16x32_bf16 v[102:105], v[146:149], v[192:195], v[102:105]
	v_mfma_f32_16x16x32_bf16 v[98:101], v[168:171], v[192:195], v[98:101]
	v_mfma_f32_16x16x32_bf16 v[86:89], v[146:149], v[200:203], v[86:89]
	v_mfma_f32_16x16x32_bf16 v[78:81], v[168:171], v[200:203], v[78:81]
	v_mfma_f32_16x16x32_bf16 v[70:73], v[146:149], v[208:211], v[70:73]
	v_mfma_f32_16x16x32_bf16 v[66:69], v[168:171], v[208:211], v[66:69]
	v_mfma_f32_16x16x32_bf16 v[110:113], v[162:165], v[188:191], v[110:113]
	v_mfma_f32_16x16x32_bf16 v[106:109], v[172:175], v[188:191], v[106:109]
	v_mfma_f32_16x16x32_bf16 v[102:105], v[162:165], v[196:199], v[102:105]
	v_mfma_f32_16x16x32_bf16 v[98:101], v[172:175], v[196:199], v[98:101]
	v_mfma_f32_16x16x32_bf16 v[86:89], v[162:165], v[204:207], v[86:89]
	v_mfma_f32_16x16x32_bf16 v[78:81], v[172:175], v[204:207], v[78:81]
	v_mfma_f32_16x16x32_bf16 v[70:73], v[162:165], v[212:215], v[70:73]
	v_mfma_f32_16x16x32_bf16 v[66:69], v[172:175], v[212:215], v[66:69]
	s_setprio 0
	s_barrier
; #define PG8_STAGE(bufoff, gbase, voff) do { _Pragma("unroll") for (int _i = 0; _i < 2; ++_i) \
;         __builtin_amdgcn_global_load_lds((const unsigned*)((const char*)(gbase) + (voff)[_i]), (LAS unsigned*)(lds + (bufoff) + ldsw + _i * 8192), 16, 0, 0); } while (0)
; #define PG8_LDA(dst, b, h) do { _Pragma("unroll") for (int m = 0; m < 4; ++m) _Pragma("unroll") for (int k = 0; k < 2; ++k) dst[m][k] = *(const LAS bf16x8*)(lds + PG8_SA(b, h) + aoff + m * 2048 + k * 1024); } while (0)
; #define PG8_LDB(dst, b, h) do { _Pragma("unroll") for (int n = 0; n < 2; ++n) _Pragma("unroll") for (int k = 0; k < 2; ++k) dst[n][k] = *(const LAS bf16x8*)(lds + PG8_SB(b, h) + boff + n * 2048 + k * 1024); } while (0)
; #define PG8_MMA(ai, bj, At, Bt) do { __builtin_amdgcn_s_setprio(1); _Pragma("unroll") for (int m = 0; m < 4; ++m) _Pragma("unroll") for (int n = 0; n < 2; ++n) _Pragma("unroll") for (int k = 0; k < 2; ++k) \
;         acc[ai][bj][m][n] = __builtin_amdgcn_mfma_f32_16x16x32_bf16(Bt[n][k], At[m][k], acc[ai][bj][m][n], 0, 0, 0); __builtin_amdgcn_s_setprio(0); } while (0)
; #define PG8_WAIT_V(n) asm volatile("s_waitcnt vmcnt(" #n ")" ::: "memory")
; #define PG8_BAR __builtin_amdgcn_s_barrier()
; template <class Epi>
; __device__ __forceinline__ void gemm_phase(LAS unsigned char* lds, const Gemm g, const StaticOrder& S, const Epi& E) {
;     ...
;             PG8_LDB(B0, 0, 0); PG8_LDB(B1, 0, 1); PG8_SCHED; PG8_LDA(At, 0, 0); PG8_STAGE(PG8_SA(1, 1), a1 + hstepA, voffA);
;             PG8_WAIT_V(8); PG8_WAIT_L(0); PG8_BAR; PG8_MMA(0, 0, At, B0); PG8_MMA(0, 1, At, B1); PG8_BAR; PG8_SCHED;
;             PG8_LDA(At, 0, 1); PG8_STAGE(PG8_SB(0, 0), b2, voffB); PG8_STAGE(PG8_SB(0, 1), b2 + hstepB, voffB); PG8_STAGE(PG8_SA(0, 0), a2, voffA);
;             PG8_WAIT_V(8); PG8_WAIT_L(0); PG8_BAR; PG8_MMA(1, 0, At, B0); PG8_MMA(1, 1, At, B1); PG8_BAR; PG8_SCHED;
;             PG8_LDB(B0, 1, 0); PG8_LDB(B1, 1, 1); PG8_SCHED; PG8_LDA(At, 1, 0); PG8_STAGE(PG8_SA(0, 1), a2 + hstepA, voffA);
;             PG8_WAIT_V(8); PG8_WAIT_L(0); PG8_BAR; PG8_MMA(0, 0, At, B0); PG8_MMA(0, 1, At, B1); PG8_BAR; PG8_SCHED;
;             PG8_LDA(At, 1, 1); PG8_STAGE(PG8_SB(1, 0), b3, voffB); PG8_STAGE(PG8_SB(1, 1), b3 + hstepB, voffB); PG8_STAGE(PG8_SA(1, 0), a3, voffA);
;             PG8_WAIT_V(8); PG8_WAIT_L(0); PG8_BAR; PG8_MMA(1, 0, At, B0); PG8_MMA(1, 1, At, B1); PG8_BAR; PG8_SCHED;
;         }
	s_add_i32 s26, s52, s30
	v_lshl_add_u64 v[184:185], v[184:185], 0, s[84:85]
	s_mov_b32 m0, s26
	ds_read_b128 v[176:179], v166 offset:49152
	ds_read_b128 v[188:191], v166 offset:50176
	ds_read_b128 v[192:195], v166 offset:51200
	ds_read_b128 v[196:199], v166 offset:52224
	ds_read_b128 v[200:203], v166 offset:53248
	ds_read_b128 v[204:207], v166 offset:54272
	ds_read_b128 v[208:211], v166 offset:55296
	ds_read_b128 v[212:215], v166 offset:56320
	global_load_lds_dwordx4 v[184:185], off
	s_add_i32 m0, s26, 0x2000
	s_add_u32 s14, s14, 0x200080
	v_lshl_add_u64 v[184:185], v[216:217], 0, s[84:85]
	s_addc_u32 s15, s15, 0
	s_add_i32 s26, s53, s30
	global_load_lds_dwordx4 v[184:185], off
	v_lshl_add_u64 v[184:185], s[14:15], 0, v[152:153]
	s_mov_b32 m0, s26
	s_nop 0
	global_load_lds_dwordx4 v[184:185], off
	v_lshl_add_u64 v[184:185], s[14:15], 0, v[156:157]
	s_add_i32 m0, s26, 0x2000
	s_nop 0
	global_load_lds_dwordx4 v[184:185], off
	v_lshl_add_u64 v[184:185], v[218:219], 0, s[84:85]
	s_mov_b32 m0, s68
	s_nop 0
	global_load_lds_dwordx4 v[184:185], off
	v_lshl_add_u64 v[184:185], v[220:221], 0, s[84:85]
	s_mov_b32 m0, s69
	s_nop 0
	global_load_lds_dwordx4 v[184:185], off
	s_waitcnt vmcnt(8)
	s_waitcnt lgkmcnt(0)
	s_barrier
	s_setprio 1
	s_waitcnt lgkmcnt(0)
	v_mfma_f32_16x16x32_bf16 v[62:65], v[130:133], v[176:179], v[62:65]
	v_mfma_f32_16x16x32_bf16 v[58:61], v[138:141], v[176:179], v[58:61]
	v_mfma_f32_16x16x32_bf16 v[50:53], v[130:133], v[192:195], v[50:53]
	v_mfma_f32_16x16x32_bf16 v[42:45], v[138:141], v[192:195], v[42:45]
	v_mfma_f32_16x16x32_bf16 v[30:33], v[130:133], v[200:203], v[30:33]
	v_mfma_f32_16x16x32_bf16 v[26:29], v[138:141], v[200:203], v[26:29]
	v_mfma_f32_16x16x32_bf16 v[18:21], v[130:133], v[208:211], v[18:21]
	v_mfma_f32_16x16x32_bf16 v[10:13], v[138:141], v[208:211], v[10:13]
	v_mfma_f32_16x16x32_bf16 v[62:65], v[134:137], v[188:191], v[62:65]
	v_mfma_f32_16x16x32_bf16 v[58:61], v[142:145], v[188:191], v[58:61]
	v_mfma_f32_16x16x32_bf16 v[50:53], v[134:137], v[196:199], v[50:53]
	v_mfma_f32_16x16x32_bf16 v[42:45], v[142:145], v[196:199], v[42:45]
	v_mfma_f32_16x16x32_bf16 v[30:33], v[134:137], v[204:207], v[30:33]
	v_mfma_f32_16x16x32_bf16 v[26:29], v[142:145], v[204:207], v[26:29]
	v_mfma_f32_16x16x32_bf16 v[18:21], v[134:137], v[212:215], v[18:21]
	v_mfma_f32_16x16x32_bf16 v[10:13], v[142:145], v[212:215], v[10:13]
	s_setprio 0
	s_setprio 1
	v_mfma_f32_16x16x32_bf16 v[54:57], v[146:149], v[176:179], v[54:57]
	v_mfma_f32_16x16x32_bf16 v[46:49], v[168:171], v[176:179], v[46:49]
	v_mfma_f32_16x16x32_bf16 v[38:41], v[146:149], v[192:195], v[38:41]
	v_mfma_f32_16x16x32_bf16 v[34:37], v[168:171], v[192:195], v[34:37]
	v_mfma_f32_16x16x32_bf16 v[22:25], v[146:149], v[200:203], v[22:25]
	v_mfma_f32_16x16x32_bf16 v[14:17], v[168:171], v[200:203], v[14:17]
	v_mfma_f32_16x16x32_bf16 v[6:9], v[146:149], v[208:211], v[6:9]
	v_mfma_f32_16x16x32_bf16 v[2:5], v[168:171], v[208:211], v[2:5]
	v_mfma_f32_16x16x32_bf16 v[54:57], v[162:165], v[188:191], v[54:57]
	v_mfma_f32_16x16x32_bf16 v[46:49], v[172:175], v[188:191], v[46:49]
	v_mfma_f32_16x16x32_bf16 v[38:41], v[162:165], v[196:199], v[38:41]
	v_mfma_f32_16x16x32_bf16 v[34:37], v[172:175], v[196:199], v[34:37]
	v_mfma_f32_16x16x32_bf16 v[22:25], v[162:165], v[204:207], v[22:25]
	v_mfma_f32_16x16x32_bf16 v[14:17], v[172:175], v[204:207], v[14:17]
	v_mfma_f32_16x16x32_bf16 v[6:9], v[162:165], v[212:215], v[6:9]
	v_mfma_f32_16x16x32_bf16 v[2:5], v[172:175], v[212:215], v[2:5]
	s_setprio 0
	s_barrier
	s_add_i32 s41, s41, 2
	s_add_u32 s24, s24, 0x100
	s_addc_u32 s25, s25, 0
	s_add_u32 s19, s19, 0x100
	s_addc_u32 s40, s40, 0
	s_cmpk_gt_u32 s41, 0x7d
	s_cbranch_scc0 .LBB0_2233
	s_cmp_ge_u32 s74, 32
	s_cbranch_scc1 .Lwpf_e
	s_lshl_b32 s100, s74, 9
	v_add_u32_e32 v130, s100, v246
	v_lshrrev_b32_e32 v131, 3, v130
	v_and_b32_e32 v130, 7, v130
	v_lshlrev_b32_e32 v130, 7, v130
	v_lshl_add_u32 v130, v131, 12, v130
	s_add_u32 s100, s88, 0x4000000
	s_addc_u32 s101, s89, 0
	s_mov_b32 m0, 0x21000
	s_nop 0
	global_load_lds_dword v130, s[100:101]

; #define PG8_STAGE(bufoff, gbase, voff) do { _Pragma("unroll") for (int _i = 0; _i < 2; ++_i) \
;         __builtin_amdgcn_global_load_lds((const unsigned*)((const char*)(gbase) + (voff)[_i]), (LAS unsigned*)(lds + (bufoff) + ldsw + _i * 8192), 16, 0, 0); } while (0)
; #define PG8_LDA(dst, b, h) do { _Pragma("unroll") for (int m = 0; m < 4; ++m) _Pragma("unroll") for (int k = 0; k < 2; ++k) dst[m][k] = *(const LAS bf16x8*)(lds + PG8_SA(b, h) + aoff + m * 2048 + k * 1024); } while (0)
; #define PG8_LDB(dst, b, h) do { _Pragma("unroll") for (int n = 0; n < 2; ++n) _Pragma("unroll") for (int k = 0; k < 2; ++k) dst[n][k] = *(const LAS bf16x8*)(lds + PG8_SB(b, h) + boff + n * 2048 + k * 1024); } while (0)
; #define PG8_MMA(ai, bj, At, Bt) do { __builtin_amdgcn_s_setprio(1); _Pragma("unroll") for (int m = 0; m < 4; ++m) _Pragma("unroll") for (int n = 0; n < 2; ++n) _Pragma("unroll") for (int k = 0; k < 2; ++k) \
;         acc[ai][bj][m][n] = __builtin_amdgcn_mfma_f32_16x16x32_bf16(Bt[n][k], At[m][k], acc[ai][bj][m][n], 0, 0, 0); __builtin_amdgcn_s_setprio(0); } while (0)
; #define PG8_WAIT_V(n) asm volatile("s_waitcnt vmcnt(" #n ")" ::: "memory")
; #define PG8_WAIT_L(n) asm volatile("s_waitcnt lgkmcnt(" #n ")" ::: "memory")
; #define PG8_BAR __builtin_amdgcn_s_barrier()
; #define PG8_SCHED __builtin_amdgcn_sched_barrier(0)
; template <class Epi>
; __device__ __forceinline__ void gemm_phase(LAS unsigned char* lds, const Gemm g, const StaticOrder& S, const Epi& E) {
;     ...
;             const bool last = (t == nt - 2);
;             const char* a1 = cA + (size_t)(t + 1) * kstep;
;             const char* a2 = last ? nA : cA + (size_t)(t + 2) * kstep; const char* b2 = last ? nB : cB + (size_t)(t + 2) * kstep;
;             const char* a3 = a2 + kstep; const char* b3 = b2 + kstep;
;             PG8_LDB(B0, 0, 0); PG8_LDB(B1, 0, 1); PG8_SCHED; PG8_LDA(At, 0, 0); PG8_STAGE(PG8_SA(1, 1), a1 + hstepA, voffA);
;             PG8_WAIT_V(8); PG8_WAIT_L(0); PG8_BAR; PG8_MMA(0, 0, At, B0); PG8_MMA(0, 1, At, B1); PG8_BAR; PG8_SCHED;
;             PG8_LDA(At, 0, 1); PG8_STAGE(PG8_SB(0, 0), b2, voffB); PG8_STAGE(PG8_SB(0, 1), b2 + hstepB, voffB); PG8_STAGE(PG8_SA(0, 0), a2, voffA);
;             PG8_WAIT_V(8); PG8_WAIT_L(0); PG8_BAR; PG8_MMA(1, 0, At, B0); PG8_MMA(1, 1, At, B1); PG8_BAR; PG8_SCHED;
.LBB0_2332:
	s_add_u32 s14, s24, 0xfff80080
	s_addc_u32 s15, s25, -1
	s_add_i32 s41, 0, 0x10000
	s_cmp_eq_u32 s40, 28
	s_cselect_b32 s27, s1, s15
	s_cselect_b32 s26, s3, s14
	s_cselect_b32 s15, s9, s33
	s_cselect_b32 s14, s17, s19
	s_add_i32 s62, 0, 0x14000
	v_add_u32_e32 v142, s41, v1
	v_add_u32_e32 v170, s62, v1
	ds_read_b128 v[130:133], v142
	ds_read_b128 v[134:137], v142 offset:1024
	ds_read_b128 v[138:141], v142 offset:2048
	ds_read_b128 v[142:145], v142 offset:3072
	ds_read_b128 v[146:149], v170
	ds_read_b128 v[150:153], v170 offset:1024
	ds_read_b128 v[166:169], v170 offset:2048
	ds_read_b128 v[170:173], v170 offset:3072
	v_lshl_add_u64 v[178:179], s[24:25], 0, v[162:163]
	s_add_i32 m0, s35, 0xc000
	ds_read_b128 v[174:177], v181
	ds_read_b128 v[188:191], v181 offset:1024
	ds_read_b128 v[192:195], v181 offset:2048
	ds_read_b128 v[196:199], v181 offset:3072
	ds_read_b128 v[200:203], v181 offset:4096
	ds_read_b128 v[204:207], v181 offset:5120
	ds_read_b128 v[208:211], v181 offset:6144
	ds_read_b128 v[212:215], v181 offset:7168
	global_load_lds_dwordx4 v[178:179], off
	v_lshl_add_u64 v[178:179], s[24:25], 0, v[164:165]
	s_add_i32 m0, s35, 0xe000
	s_nop 0
	global_load_lds_dwordx4 v[178:179], off
	s_waitcnt vmcnt(8)
	s_waitcnt lgkmcnt(0)
	s_barrier
	s_setprio 1
	s_waitcnt lgkmcnt(0)
	v_mfma_f32_16x16x32_bf16 v[126:129], v[130:133], v[174:177], v[126:129]
	v_mfma_f32_16x16x32_bf16 v[122:125], v[138:141], v[174:177], v[122:125]
	v_mfma_f32_16x16x32_bf16 v[118:121], v[130:133], v[192:195], v[118:121]
	v_mfma_f32_16x16x32_bf16 v[114:117], v[138:141], v[192:195], v[114:117]
	v_mfma_f32_16x16x32_bf16 v[102:105], v[130:133], v[200:203], v[102:105]
	v_mfma_f32_16x16x32_bf16 v[98:101], v[138:141], v[200:203], v[98:101]
	v_mfma_f32_16x16x32_bf16 v[86:89], v[130:133], v[208:211], v[86:89]
	v_mfma_f32_16x16x32_bf16 v[82:85], v[138:141], v[208:211], v[82:85]
	v_mfma_f32_16x16x32_bf16 v[126:129], v[134:137], v[188:191], v[126:129]
	v_mfma_f32_16x16x32_bf16 v[122:125], v[142:145], v[188:191], v[122:125]
	v_mfma_f32_16x16x32_bf16 v[118:121], v[134:137], v[196:199], v[118:121]
	v_mfma_f32_16x16x32_bf16 v[114:117], v[142:145], v[196:199], v[114:117]
	v_mfma_f32_16x16x32_bf16 v[102:105], v[134:137], v[204:207], v[102:105]
	v_mfma_f32_16x16x32_bf16 v[98:101], v[142:145], v[204:207], v[98:101]
	v_mfma_f32_16x16x32_bf16 v[86:89], v[134:137], v[212:215], v[86:89]
	v_mfma_f32_16x16x32_bf16 v[82:85], v[142:145], v[212:215], v[82:85]
	s_setprio 0
	s_setprio 1
	v_mfma_f32_16x16x32_bf16 v[110:113], v[146:149], v[174:177], v[110:113]
	v_mfma_f32_16x16x32_bf16 v[106:109], v[166:169], v[174:177], v[106:109]
	v_mfma_f32_16x16x32_bf16 v[94:97], v[146:149], v[192:195], v[94:97]
	v_mfma_f32_16x16x32_bf16 v[90:93], v[166:169], v[192:195], v[90:93]
	v_mfma_f32_16x16x32_bf16 v[78:81], v[146:149], v[200:203], v[78:81]
	v_mfma_f32_16x16x32_bf16 v[74:77], v[166:169], v[200:203], v[74:77]
	v_mfma_f32_16x16x32_bf16 v[70:73], v[146:149], v[208:211], v[70:73]
	v_mfma_f32_16x16x32_bf16 v[66:69], v[166:169], v[208:211], v[66:69]
	v_mfma_f32_16x16x32_bf16 v[110:113], v[150:153], v[188:191], v[110:113]
	v_mfma_f32_16x16x32_bf16 v[106:109], v[170:173], v[188:191], v[106:109]
	v_mfma_f32_16x16x32_bf16 v[94:97], v[150:153], v[196:199], v[94:97]
	v_mfma_f32_16x16x32_bf16 v[90:93], v[170:173], v[196:199], v[90:93]
	v_mfma_f32_16x16x32_bf16 v[78:81], v[150:153], v[204:207], v[78:81]
	v_mfma_f32_16x16x32_bf16 v[74:77], v[170:173], v[204:207], v[74:77]
	v_mfma_f32_16x16x32_bf16 v[70:73], v[150:153], v[212:215], v[70:73]
	v_mfma_f32_16x16x32_bf16 v[66:69], v[170:173], v[212:215], v[66:69]
	s_setprio 0
	s_barrier
	s_add_i32 s41, s41, s34
	v_lshl_add_u64 v[178:179], s[14:15], 0, v[156:157]
	s_mov_b32 m0, s41
	ds_read_b128 v[174:177], v181 offset:16384
	ds_read_b128 v[188:191], v181 offset:17408
	ds_read_b128 v[192:195], v181 offset:18432
	ds_read_b128 v[196:199], v181 offset:19456
	ds_read_b128 v[200:203], v181 offset:20480
	ds_read_b128 v[204:207], v181 offset:21504
	ds_read_b128 v[208:211], v181 offset:22528
	ds_read_b128 v[212:215], v181 offset:23552
	global_load_lds_dwordx4 v[178:179], off
	s_add_i32 m0, s41, 0x2000
	s_add_u32 s52, s14, 0x80000
	v_lshl_add_u64 v[184:185], s[14:15], 0, v[160:161]
	s_addc_u32 s53, s15, 0
	s_add_i32 s41, s62, s34
	global_load_lds_dwordx4 v[184:185], off
	v_lshl_add_u64 v[216:217], s[52:53], 0, v[156:157]
	s_mov_b32 m0, s41
	v_lshl_add_u64 v[218:219], s[26:27], 0, v[158:159]
	global_load_lds_dwordx4 v[216:217], off
	v_lshl_add_u64 v[216:217], s[52:53], 0, v[160:161]
	s_add_i32 m0, s41, 0x2000
	s_nop 0
	global_load_lds_dwordx4 v[216:217], off
	v_lshl_add_u64 v[216:217], s[26:27], 0, v[154:155]
	s_mov_b32 m0, s35
	s_nop 0
	global_load_lds_dwordx4 v[216:217], off
	s_mov_b32 m0, s42
	s_nop 0
	global_load_lds_dwordx4 v[218:219], off
	s_waitcnt vmcnt(8)
	s_waitcnt lgkmcnt(0)
	s_barrier
; #define PG8_STAGE(bufoff, gbase, voff) do { _Pragma("unroll") for (int _i = 0; _i < 2; ++_i) \
;         __builtin_amdgcn_global_load_lds((const unsigned*)((const char*)(gbase) + (voff)[_i]), (LAS unsigned*)(lds + (bufoff) + ldsw + _i * 8192), 16, 0, 0); } while (0)
; #define PG8_LDA(dst, b, h) do { _Pragma("unroll") for (int m = 0; m < 4; ++m) _Pragma("unroll") for (int k = 0; k < 2; ++k) dst[m][k] = *(const LAS bf16x8*)(lds + PG8_SA(b, h) + aoff + m * 2048 + k * 1024); } while (0)
; #define PG8_LDB(dst, b, h) do { _Pragma("unroll") for (int n = 0; n < 2; ++n) _Pragma("unroll") for (int k = 0; k < 2; ++k) dst[n][k] = *(const LAS bf16x8*)(lds + PG8_SB(b, h) + boff + n * 2048 + k * 1024); } while (0)
; #define PG8_MMA(ai, bj, At, Bt) do { __builtin_amdgcn_s_setprio(1); _Pragma("unroll") for (int m = 0; m < 4; ++m) _Pragma("unroll") for (int n = 0; n < 2; ++n) _Pragma("unroll") for (int k = 0; k < 2; ++k) \
;         acc[ai][bj][m][n] = __builtin_amdgcn_mfma_f32_16x16x32_bf16(Bt[n][k], At[m][k], acc[ai][bj][m][n], 0, 0, 0); __builtin_amdgcn_s_setprio(0); } while (0)
; #define PG8_WAIT_V(n) asm volatile("s_waitcnt vmcnt(" #n ")" ::: "memory")
; #define PG8_WAIT_L(n) asm volatile("s_waitcnt lgkmcnt(" #n ")" ::: "memory")
; #define PG8_BAR __builtin_amdgcn_s_barrier()
; #define PG8_SCHED __builtin_amdgcn_sched_barrier(0)
; template <class Epi>
; __device__ __forceinline__ void gemm_phase(LAS unsigned char* lds, const Gemm g, const StaticOrder& S, const Epi& E) {
;     ...
;             PG8_WAIT_V(8); PG8_WAIT_L(0); PG8_BAR; PG8_MMA(1, 0, At, B0); PG8_MMA(1, 1, At, B1); PG8_BAR; PG8_SCHED;
;             PG8_LDB(B0, 1, 0); PG8_LDB(B1, 1, 1); PG8_SCHED; PG8_LDA(At, 1, 0); PG8_STAGE(PG8_SA(0, 1), a2 + hstepA, voffA);
;             PG8_WAIT_V(8); PG8_WAIT_L(0); PG8_BAR; PG8_MMA(0, 0, At, B0); PG8_MMA(0, 1, At, B1); PG8_BAR; PG8_SCHED;
	s_setprio 1
	s_waitcnt lgkmcnt(0)
	v_mfma_f32_16x16x32_bf16 v[62:65], v[130:133], v[174:177], v[62:65]
	v_mfma_f32_16x16x32_bf16 v[58:61], v[138:141], v[174:177], v[58:61]
	v_mfma_f32_16x16x32_bf16 v[54:57], v[130:133], v[192:195], v[54:57]
	v_mfma_f32_16x16x32_bf16 v[50:53], v[138:141], v[192:195], v[50:53]
	v_mfma_f32_16x16x32_bf16 v[46:49], v[130:133], v[200:203], v[46:49]
	v_mfma_f32_16x16x32_bf16 v[38:41], v[138:141], v[200:203], v[38:41]
	v_mfma_f32_16x16x32_bf16 v[30:33], v[130:133], v[208:211], v[30:33]
	v_mfma_f32_16x16x32_bf16 v[22:25], v[138:141], v[208:211], v[22:25]
	v_mfma_f32_16x16x32_bf16 v[62:65], v[134:137], v[188:191], v[62:65]
	v_mfma_f32_16x16x32_bf16 v[58:61], v[142:145], v[188:191], v[58:61]
	v_mfma_f32_16x16x32_bf16 v[54:57], v[134:137], v[196:199], v[54:57]
	v_mfma_f32_16x16x32_bf16 v[50:53], v[142:145], v[196:199], v[50:53]
	v_mfma_f32_16x16x32_bf16 v[46:49], v[134:137], v[204:207], v[46:49]
	v_mfma_f32_16x16x32_bf16 v[38:41], v[142:145], v[204:207], v[38:41]
	v_mfma_f32_16x16x32_bf16 v[30:33], v[134:137], v[212:215], v[30:33]
	v_mfma_f32_16x16x32_bf16 v[22:25], v[142:145], v[212:215], v[22:25]
	s_setprio 0
	s_setprio 1
	v_mfma_f32_16x16x32_bf16 v[42:45], v[146:149], v[174:177], v[42:45]
	v_mfma_f32_16x16x32_bf16 v[34:37], v[166:169], v[174:177], v[34:37]
	v_mfma_f32_16x16x32_bf16 v[26:29], v[146:149], v[192:195], v[26:29]
	v_mfma_f32_16x16x32_bf16 v[18:21], v[166:169], v[192:195], v[18:21]
	v_mfma_f32_16x16x32_bf16 v[14:17], v[146:149], v[200:203], v[14:17]
	v_mfma_f32_16x16x32_bf16 v[10:13], v[166:169], v[200:203], v[10:13]
	v_mfma_f32_16x16x32_bf16 v[6:9], v[146:149], v[208:211], v[6:9]
	v_mfma_f32_16x16x32_bf16 v[2:5], v[166:169], v[208:211], v[2:5]
	v_mfma_f32_16x16x32_bf16 v[42:45], v[150:153], v[188:191], v[42:45]
	v_mfma_f32_16x16x32_bf16 v[34:37], v[170:173], v[188:191], v[34:37]
	v_mfma_f32_16x16x32_bf16 v[26:29], v[150:153], v[196:199], v[26:29]
	v_mfma_f32_16x16x32_bf16 v[18:21], v[170:173], v[196:199], v[18:21]
	v_mfma_f32_16x16x32_bf16 v[14:17], v[150:153], v[204:207], v[14:17]
	v_mfma_f32_16x16x32_bf16 v[10:13], v[170:173], v[204:207], v[10:13]
	v_mfma_f32_16x16x32_bf16 v[6:9], v[150:153], v[212:215], v[6:9]
	v_mfma_f32_16x16x32_bf16 v[2:5], v[170:173], v[212:215], v[2:5]
	s_setprio 0
	s_barrier
	s_add_i32 s41, 0, 0x18000
	s_add_i32 s52, 0, 0x1c000
	v_add_u32_e32 v142, s41, v1
	v_add_u32_e32 v170, s52, v1
	ds_read_b128 v[130:133], v142
	ds_read_b128 v[134:137], v142 offset:1024
	ds_read_b128 v[138:141], v142 offset:2048
	ds_read_b128 v[142:145], v142 offset:3072
	ds_read_b128 v[146:149], v170
	ds_read_b128 v[150:153], v170 offset:1024
	ds_read_b128 v[166:169], v170 offset:2048
	ds_read_b128 v[170:173], v170 offset:3072
	s_add_u32 s26, s26, 0x80000
	s_addc_u32 s27, s27, 0
	s_mov_b32 m0, s44
	v_lshl_add_u64 v[220:221], s[26:27], 0, v[154:155]
	ds_read_b128 v[174:177], v181 offset:32768
	ds_read_b128 v[188:191], v181 offset:33792
	ds_read_b128 v[192:195], v181 offset:34816
	ds_read_b128 v[196:199], v181 offset:35840
	ds_read_b128 v[200:203], v181 offset:36864
	ds_read_b128 v[204:207], v181 offset:37888
	ds_read_b128 v[208:211], v181 offset:38912
	ds_read_b128 v[212:215], v181 offset:39936
	global_load_lds_dwordx4 v[220:221], off
	v_lshl_add_u64 v[220:221], s[26:27], 0, v[158:159]
	s_mov_b32 m0, s45
	s_nop 0
	global_load_lds_dwordx4 v[220:221], off
	s_waitcnt vmcnt(8)
	s_waitcnt lgkmcnt(0)
	s_barrier
	s_setprio 1
	s_waitcnt lgkmcnt(0)
	v_mfma_f32_16x16x32_bf16 v[126:129], v[130:133], v[174:177], v[126:129]
	v_mfma_f32_16x16x32_bf16 v[122:125], v[138:141], v[174:177], v[122:125]
	v_mfma_f32_16x16x32_bf16 v[118:121], v[130:133], v[192:195], v[118:121]
	v_mfma_f32_16x16x32_bf16 v[114:117], v[138:141], v[192:195], v[114:117]
	v_mfma_f32_16x16x32_bf16 v[102:105], v[130:133], v[200:203], v[102:105]
	v_mfma_f32_16x16x32_bf16 v[98:101], v[138:141], v[200:203], v[98:101]
	v_mfma_f32_16x16x32_bf16 v[86:89], v[130:133], v[208:211], v[86:89]
	v_mfma_f32_16x16x32_bf16 v[82:85], v[138:141], v[208:211], v[82:85]
	v_mfma_f32_16x16x32_bf16 v[126:129], v[134:137], v[188:191], v[126:129]
	v_mfma_f32_16x16x32_bf16 v[122:125], v[142:145], v[188:191], v[122:125]
	v_mfma_f32_16x16x32_bf16 v[118:121], v[134:137], v[196:199], v[118:121]
	v_mfma_f32_16x16x32_bf16 v[114:117], v[142:145], v[196:199], v[114:117]
	v_mfma_f32_16x16x32_bf16 v[102:105], v[134:137], v[204:207], v[102:105]
	v_mfma_f32_16x16x32_bf16 v[98:101], v[142:145], v[204:207], v[98:101]
	v_mfma_f32_16x16x32_bf16 v[86:89], v[134:137], v[212:215], v[86:89]
	v_mfma_f32_16x16x32_bf16 v[82:85], v[142:145], v[212:215], v[82:85]
	s_setprio 0
	s_setprio 1
	v_mfma_f32_16x16x32_bf16 v[110:113], v[146:149], v[174:177], v[110:113]
	v_mfma_f32_16x16x32_bf16 v[106:109], v[166:169], v[174:177], v[106:109]
	v_mfma_f32_16x16x32_bf16 v[94:97], v[146:149], v[192:195], v[94:97]
	v_mfma_f32_16x16x32_bf16 v[90:93], v[166:169], v[192:195], v[90:93]
	v_mfma_f32_16x16x32_bf16 v[78:81], v[146:149], v[200:203], v[78:81]
	v_mfma_f32_16x16x32_bf16 v[74:77], v[166:169], v[200:203], v[74:77]
	v_mfma_f32_16x16x32_bf16 v[70:73], v[146:149], v[208:211], v[70:73]
	v_mfma_f32_16x16x32_bf16 v[66:69], v[166:169], v[208:211], v[66:69]
	v_mfma_f32_16x16x32_bf16 v[110:113], v[150:153], v[188:191], v[110:113]
	v_mfma_f32_16x16x32_bf16 v[106:109], v[170:173], v[188:191], v[106:109]
	v_mfma_f32_16x16x32_bf16 v[94:97], v[150:153], v[196:199], v[94:97]
	v_mfma_f32_16x16x32_bf16 v[90:93], v[170:173], v[196:199], v[90:93]
	v_mfma_f32_16x16x32_bf16 v[78:81], v[150:153], v[204:207], v[78:81]
	v_mfma_f32_16x16x32_bf16 v[74:77], v[170:173], v[204:207], v[74:77]
	v_mfma_f32_16x16x32_bf16 v[70:73], v[150:153], v[212:215], v[70:73]
	v_mfma_f32_16x16x32_bf16 v[66:69], v[170:173], v[212:215], v[66:69]
	s_setprio 0
	s_barrier
; #define PG8_STAGE(bufoff, gbase, voff) do { _Pragma("unroll") for (int _i = 0; _i < 2; ++_i) \
;         __builtin_amdgcn_global_load_lds((const unsigned*)((const char*)(gbase) + (voff)[_i]), (LAS unsigned*)(lds + (bufoff) + ldsw + _i * 8192), 16, 0, 0); } while (0)
; #define PG8_LDA(dst, b, h) do { _Pragma("unroll") for (int m = 0; m < 4; ++m) _Pragma("unroll") for (int k = 0; k < 2; ++k) dst[m][k] = *(const LAS bf16x8*)(lds + PG8_SA(b, h) + aoff + m * 2048 + k * 1024); } while (0)
; #define PG8_MMA(ai, bj, At, Bt) do { __builtin_amdgcn_s_setprio(1); _Pragma("unroll") for (int m = 0; m < 4; ++m) _Pragma("unroll") for (int n = 0; n < 2; ++n) _Pragma("unroll") for (int k = 0; k < 2; ++k) \
;         acc[ai][bj][m][n] = __builtin_amdgcn_mfma_f32_16x16x32_bf16(Bt[n][k], At[m][k], acc[ai][bj][m][n], 0, 0, 0); __builtin_amdgcn_s_setprio(0); } while (0)
; #define PG8_WAIT_V(n) asm volatile("s_waitcnt vmcnt(" #n ")" ::: "memory")
; #define PG8_WAIT_L(n) asm volatile("s_waitcnt lgkmcnt(" #n ")" ::: "memory")
; #define PG8_BAR __builtin_amdgcn_s_barrier()
; #define PG8_SCHED __builtin_amdgcn_sched_barrier(0)
; template <class Epi>
; __device__ __forceinline__ void gemm_phase(LAS unsigned char* lds, const Gemm g, const StaticOrder& S, const Epi& E) {
;     ...
;             PG8_LDA(At, 1, 1); PG8_STAGE(PG8_SB(1, 0), b3, voffB); PG8_STAGE(PG8_SB(1, 1), b3 + hstepB, voffB); PG8_STAGE(PG8_SA(1, 0), a3, voffA);
;             PG8_WAIT_V(8); PG8_WAIT_L(0); PG8_BAR; PG8_MMA(1, 0, At, B0); PG8_MMA(1, 1, At, B1); PG8_BAR; PG8_SCHED;
	s_add_i32 s26, s41, s34
	v_lshl_add_u64 v[178:179], v[178:179], 0, s[84:85]
	s_mov_b32 m0, s26
	ds_read_b128 v[174:177], v181 offset:49152
	ds_read_b128 v[188:191], v181 offset:50176
	ds_read_b128 v[192:195], v181 offset:51200
	ds_read_b128 v[196:199], v181 offset:52224
	ds_read_b128 v[200:203], v181 offset:53248
	ds_read_b128 v[204:207], v181 offset:54272
	ds_read_b128 v[208:211], v181 offset:55296
	ds_read_b128 v[212:215], v181 offset:56320
	global_load_lds_dwordx4 v[178:179], off
	s_add_i32 m0, s26, 0x2000
	s_add_u32 s14, s14, 0x80080
	v_lshl_add_u64 v[178:179], v[184:185], 0, s[84:85]
	s_addc_u32 s15, s15, 0
	s_add_i32 s26, s52, s34
	global_load_lds_dwordx4 v[178:179], off
	v_lshl_add_u64 v[178:179], s[14:15], 0, v[156:157]
	s_mov_b32 m0, s26
	s_nop 0
	global_load_lds_dwordx4 v[178:179], off
	v_lshl_add_u64 v[178:179], s[14:15], 0, v[160:161]
	s_add_i32 m0, s26, 0x2000
	s_nop 0
	global_load_lds_dwordx4 v[178:179], off
	v_lshl_add_u64 v[178:179], v[216:217], 0, s[84:85]
	s_mov_b32 m0, s86
	s_nop 0
	global_load_lds_dwordx4 v[178:179], off
	v_lshl_add_u64 v[178:179], v[218:219], 0, s[84:85]
	s_mov_b32 m0, s87
	s_nop 0
	global_load_lds_dwordx4 v[178:179], off
	s_waitcnt vmcnt(8)
	s_waitcnt lgkmcnt(0)
	s_barrier
	s_setprio 1
	s_waitcnt lgkmcnt(0)
	v_mfma_f32_16x16x32_bf16 v[62:65], v[130:133], v[174:177], v[62:65]
	v_mfma_f32_16x16x32_bf16 v[58:61], v[138:141], v[174:177], v[58:61]
	v_mfma_f32_16x16x32_bf16 v[54:57], v[130:133], v[192:195], v[54:57]
	v_mfma_f32_16x16x32_bf16 v[50:53], v[138:141], v[192:195], v[50:53]
	v_mfma_f32_16x16x32_bf16 v[46:49], v[130:133], v[200:203], v[46:49]
	v_mfma_f32_16x16x32_bf16 v[38:41], v[138:141], v[200:203], v[38:41]
	v_mfma_f32_16x16x32_bf16 v[30:33], v[130:133], v[208:211], v[30:33]
	v_mfma_f32_16x16x32_bf16 v[22:25], v[138:141], v[208:211], v[22:25]
	v_mfma_f32_16x16x32_bf16 v[62:65], v[134:137], v[188:191], v[62:65]
	v_mfma_f32_16x16x32_bf16 v[58:61], v[142:145], v[188:191], v[58:61]
	v_mfma_f32_16x16x32_bf16 v[54:57], v[134:137], v[196:199], v[54:57]
	v_mfma_f32_16x16x32_bf16 v[50:53], v[142:145], v[196:199], v[50:53]
	v_mfma_f32_16x16x32_bf16 v[46:49], v[134:137], v[204:207], v[46:49]
	v_mfma_f32_16x16x32_bf16 v[38:41], v[142:145], v[204:207], v[38:41]
	v_mfma_f32_16x16x32_bf16 v[30:33], v[134:137], v[212:215], v[30:33]
	v_mfma_f32_16x16x32_bf16 v[22:25], v[142:145], v[212:215], v[22:25]
	s_setprio 0
	s_setprio 1
	v_mfma_f32_16x16x32_bf16 v[42:45], v[146:149], v[174:177], v[42:45]
	v_mfma_f32_16x16x32_bf16 v[34:37], v[166:169], v[174:177], v[34:37]
	v_mfma_f32_16x16x32_bf16 v[26:29], v[146:149], v[192:195], v[26:29]
	v_mfma_f32_16x16x32_bf16 v[18:21], v[166:169], v[192:195], v[18:21]
	v_mfma_f32_16x16x32_bf16 v[14:17], v[146:149], v[200:203], v[14:17]
	v_mfma_f32_16x16x32_bf16 v[10:13], v[166:169], v[200:203], v[10:13]
	v_mfma_f32_16x16x32_bf16 v[6:9], v[146:149], v[208:211], v[6:9]
	v_mfma_f32_16x16x32_bf16 v[2:5], v[166:169], v[208:211], v[2:5]
	v_mfma_f32_16x16x32_bf16 v[42:45], v[150:153], v[188:191], v[42:45]
	v_mfma_f32_16x16x32_bf16 v[34:37], v[170:173], v[188:191], v[34:37]
	v_mfma_f32_16x16x32_bf16 v[26:29], v[150:153], v[196:199], v[26:29]
	v_mfma_f32_16x16x32_bf16 v[18:21], v[170:173], v[196:199], v[18:21]
	v_mfma_f32_16x16x32_bf16 v[14:17], v[150:153], v[204:207], v[14:17]
	v_mfma_f32_16x16x32_bf16 v[10:13], v[170:173], v[204:207], v[10:13]
	v_mfma_f32_16x16x32_bf16 v[6:9], v[150:153], v[212:215], v[6:9]
	v_mfma_f32_16x16x32_bf16 v[2:5], v[170:173], v[212:215], v[2:5]
	s_setprio 0
	s_barrier
	s_add_i32 s40, s40, 2
	s_add_u32 s24, s24, 0x100
	s_addc_u32 s25, s25, 0
	s_add_u32 s19, s19, 0x100
	s_addc_u32 s33, s33, 0
	s_cmp_gt_u32 s40, 29
	s_cbranch_scc0 .LBB0_2332
	s_cmp_ge_u32 s74, 32
	s_cbranch_scc1 .Lwpf_f
	s_lshl_b32 s100, s74, 9
	v_add_u32_e32 v130, s100, v246
	v_lshrrev_b32_e32 v131, 3, v130
	v_and_b32_e32 v130, 7, v130
	v_lshlrev_b32_e32 v130, 7, v130
	v_lshl_add_u32 v130, v131, 12, v130
	v_readlane_b32 s100, v255, 42
	s_nop 3
	s_mov_b32 s101, 0x16900000
	s_cmp_eq_u32 s100, 1
	s_cselect_b32 s101, 0x15100000, s101
	s_cmp_eq_u32 s100, 0
	s_cselect_b32 s101, 0x13700000, s101
	s_add_u32 s100, s38, s101
	s_addc_u32 s101, s39, 0
	s_mov_b32 m0, 0x21000
	s_nop 0
	global_load_lds_dword v130, s[100:101]
